# code placement: heads of the attention steady loop and the three GEMM K-loops aligned to 64 bytes
# baseline (speedup 1.0000x reference)
; #define PG8_STAGE(bufoff, gbase, voff) do { _Pragma("unroll") for (int _i = 0; _i < 2; ++_i) \
;         __builtin_amdgcn_global_load_lds((const unsigned*)((const char*)(gbase) + (voff)[_i]), (PG8_LAS unsigned*)(lds + (bufoff) + ldsw + _i * 8192), 16, 0, 0); } while (0)
; #define PG8_LDA(dst, b, h) do { _Pragma("unroll") for (int m = 0; m < 4; ++m) _Pragma("unroll") for (int k = 0; k < 2; ++k) dst[m][k] = *(const PG8_LAS bf16x8*)(lds + PG8_SA(b, h) + aoff + m * 2048 + k * 1024); } while (0)
; #define PG8_LDB(dst, b, h) do { _Pragma("unroll") for (int n = 0; n < 2; ++n) _Pragma("unroll") for (int k = 0; k < 2; ++k) dst[n][k] = *(const PG8_LAS bf16x8*)(lds + PG8_SB(b, h) + boff + n * 2048 + k * 1024); } while (0)
; #define PG8_WAIT_V(n) asm volatile("s_waitcnt vmcnt(" #n ")" ::: "memory")
; #define PG8_WAIT_L(n) asm volatile("s_waitcnt lgkmcnt(" #n ")" ::: "memory")
; #define PG8_BAR __builtin_amdgcn_s_barrier()
; #define PG8_SCHED __builtin_amdgcn_sched_barrier(0)
; template <class Epi, class Sched, bool ALIGN_EPI = false, bool SP2 = false>
; __device__ __forceinline__ void gemm_phase(PG8_LAS unsigned char* lds, const Gemm g, const Sched& S, const Epi& E) {
;     ...
;         const char* nA = has_next ? (const char*)g.A + (size_t)nxt.pm * tstep : cA; const char* nB = has_next ? (const char*)g.Bt + (size_t)nxt.pn * tstep : cB;
;         for (int t = 0; t < nt; t += 2) {
;             if constexpr (Epi::MID) { if (t == nt / 2) E.mid(acc, cur, wr, wc, fr, fq); }
;             const bool last = (t == nt - 2);
;             const char* a1 = cA + (size_t)(t + 1) * kstep;
;             const char* a2 = last ? nA : cA + (size_t)(t + 2) * kstep; const char* b2 = last ? nB : cB + (size_t)(t + 2) * kstep;
;             const char* a3 = a2 + kstep; const char* b3 = b2 + kstep;
;             if (last && has_next) S.a_ready(nxt);
;             if constexpr (SP2) {
;             PG8_LDB(B0, 0, 0); PG8_LDB(B1, 0, 1); PG8_SCHED; PG8_LDA(At, 0, 0); PG8_STAGE(PG8_SA(1, 1), a1 + hstep, voffA);
;             PG8_WAIT_V(8); PG8_WAIT_L(0); PG8_BAR; PG8_MMA(0, 0, At, B0); PG8_MMA(0, 1, At, B1); PG8_BAR; PG8_SCHED;
;             PG8_LDA(At, 0, 1); PG8_STAGE(PG8_SB(0, 0), b2, voffB); PG8_STAGE(PG8_SB(0, 1), b2 + hstep, voffB); PG8_STAGE(PG8_SA(0, 0), a2, voffA);
;             PG8_WAIT_V(8); PG8_WAIT_L(0); PG8_BAR; PG8_MMA(1, 0, At, B0); PG8_MMA(1, 1, At, B1); PG8_BAR; PG8_SCHED;
.LBB0_233:
	s_ashr_i32 s35, s34, 31
	s_lshl_b64 s[36:37], s[34:35], 19
	s_add_u32 s36, s49, s36
	s_addc_u32 s37, s50, s37
	s_and_b64 s[38:39], s[4:5], exec
	s_cselect_b32 s7, s37, s43
	s_cselect_b32 s35, s36, s42
	s_ashr_i32 s31, s30, 31
	s_lshl_b64 s[38:39], s[30:31], 19
	s_add_u32 s38, s33, s38
	s_addc_u32 s39, s48, s39
	s_and_b64 s[46:47], s[4:5], exec
	s_cselect_b32 s31, s39, s45
	s_cselect_b32 s77, s38, s44
	s_add_u32 s42, s42, 0x40080
	s_addc_u32 s43, s43, 0
	s_add_u32 s78, s44, 0x100
	s_addc_u32 s79, s45, 0
	s_mov_b32 s80, -2
	ds_read_b128 v[152:155], v176
	ds_read_b128 v[156:159], v176 offset:1024
	ds_read_b128 v[160:163], v176 offset:2048
	ds_read_b128 v[182:185], v176 offset:3072
	ds_read_b128 v[186:189], v177
	ds_read_b128 v[190:193], v177 offset:1024
	ds_read_b128 v[194:197], v177 offset:2048
	ds_read_b128 v[198:201], v177 offset:3072
	s_add_u32 s44, s42, 0xfffc0080
	s_addc_u32 s45, s43, -1
	s_cmp_eq_u32 s80, 12
	s_cselect_b32 s47, s7, s45
	s_cselect_b32 s46, s35, s44
	s_cselect_b32 s45, s31, s79
	s_cselect_b32 s44, s77, s78
	v_lshl_add_u64 v[234:235], s[42:43], 0, v[144:145]
	s_add_i32 m0, s41, 0xc000
	ds_read_b128 v[202:205], v178
	ds_read_b128 v[206:209], v178 offset:1024
	ds_read_b128 v[210:213], v178 offset:2048
	ds_read_b128 v[214:217], v178 offset:3072
	ds_read_b128 v[218:221], v178 offset:4096
	ds_read_b128 v[222:225], v178 offset:5120
	ds_read_b128 v[226:229], v178 offset:6144
	ds_read_b128 v[230:233], v178 offset:7168
	global_load_lds_dwordx4 v[234:235], off
	v_lshl_add_u64 v[234:235], s[42:43], 0, v[146:147]
	s_add_i32 m0, s41, 0xe000
	s_nop 0
	global_load_lds_dwordx4 v[234:235], off
	s_waitcnt vmcnt(8)
	s_waitcnt lgkmcnt(0)
	s_barrier
	s_setprio 1
	s_waitcnt lgkmcnt(0)
	v_mfma_f32_16x16x32_bf16 v[126:129], v[152:155], v[202:205], 0
	v_mfma_f32_16x16x32_bf16 v[122:125], v[160:163], v[202:205], 0
	v_mfma_f32_16x16x32_bf16 v[114:117], v[152:155], v[210:213], 0
	v_mfma_f32_16x16x32_bf16 v[110:113], v[160:163], v[210:213], 0
	v_mfma_f32_16x16x32_bf16 v[98:101], v[152:155], v[218:221], 0
	v_mfma_f32_16x16x32_bf16 v[94:97], v[160:163], v[218:221], 0
	v_mfma_f32_16x16x32_bf16 v[82:85], v[152:155], v[226:229], 0
	v_mfma_f32_16x16x32_bf16 v[78:81], v[160:163], v[226:229], 0
	v_mfma_f32_16x16x32_bf16 v[126:129], v[156:159], v[206:209], v[126:129]
	v_mfma_f32_16x16x32_bf16 v[122:125], v[182:185], v[206:209], v[122:125]
	v_mfma_f32_16x16x32_bf16 v[114:117], v[156:159], v[214:217], v[114:117]
	v_mfma_f32_16x16x32_bf16 v[110:113], v[182:185], v[214:217], v[110:113]
	v_mfma_f32_16x16x32_bf16 v[98:101], v[156:159], v[222:225], v[98:101]
	v_mfma_f32_16x16x32_bf16 v[94:97], v[182:185], v[222:225], v[94:97]
	v_mfma_f32_16x16x32_bf16 v[82:85], v[156:159], v[230:233], v[82:85]
	v_mfma_f32_16x16x32_bf16 v[78:81], v[182:185], v[230:233], v[78:81]
	s_setprio 0
	s_setprio 1
	v_mfma_f32_16x16x32_bf16 v[118:121], v[186:189], v[202:205], 0
	v_mfma_f32_16x16x32_bf16 v[106:109], v[194:197], v[202:205], 0
	v_mfma_f32_16x16x32_bf16 v[102:105], v[186:189], v[210:213], 0
	v_mfma_f32_16x16x32_bf16 v[90:93], v[194:197], v[210:213], 0
	v_mfma_f32_16x16x32_bf16 v[86:89], v[186:189], v[218:221], 0
	v_mfma_f32_16x16x32_bf16 v[74:77], v[194:197], v[218:221], 0
	v_mfma_f32_16x16x32_bf16 v[70:73], v[186:189], v[226:229], 0
	v_mfma_f32_16x16x32_bf16 v[66:69], v[194:197], v[226:229], 0
	v_mfma_f32_16x16x32_bf16 v[118:121], v[190:193], v[206:209], v[118:121]
	v_mfma_f32_16x16x32_bf16 v[106:109], v[198:201], v[206:209], v[106:109]
	v_mfma_f32_16x16x32_bf16 v[102:105], v[190:193], v[214:217], v[102:105]
	v_mfma_f32_16x16x32_bf16 v[90:93], v[198:201], v[214:217], v[90:93]
	v_mfma_f32_16x16x32_bf16 v[86:89], v[190:193], v[222:225], v[86:89]
	v_mfma_f32_16x16x32_bf16 v[74:77], v[198:201], v[222:225], v[74:77]
	v_mfma_f32_16x16x32_bf16 v[70:73], v[190:193], v[230:233], v[70:73]
	v_mfma_f32_16x16x32_bf16 v[66:69], v[198:201], v[230:233], v[66:69]
	s_setprio 0
	s_barrier
	s_add_i32 s81, s64, s15
	v_lshl_add_u64 v[234:235], s[44:45], 0, v[132:133]
	s_mov_b32 m0, s81
	ds_read_b128 v[202:205], v178 offset:16384
	ds_read_b128 v[206:209], v178 offset:17408
	ds_read_b128 v[210:213], v178 offset:18432
	ds_read_b128 v[214:217], v178 offset:19456
	ds_read_b128 v[218:221], v178 offset:20480
	ds_read_b128 v[222:225], v178 offset:21504
	ds_read_b128 v[226:229], v178 offset:22528
	ds_read_b128 v[230:233], v178 offset:23552
	global_load_lds_dwordx4 v[234:235], off
	s_add_i32 m0, s81, 0x2000
	s_add_u32 s82, s44, 0x40000
	v_lshl_add_u64 v[236:237], s[44:45], 0, v[136:137]
	s_addc_u32 s83, s45, 0
	s_add_i32 s81, s65, s15
	global_load_lds_dwordx4 v[236:237], off
	v_lshl_add_u64 v[238:239], s[82:83], 0, v[132:133]
	s_mov_b32 m0, s81
	v_lshl_add_u64 v[240:241], s[46:47], 0, v[134:135]
	global_load_lds_dwordx4 v[238:239], off
	v_lshl_add_u64 v[238:239], s[82:83], 0, v[136:137]
	s_add_i32 m0, s81, 0x2000
	s_nop 0
	global_load_lds_dwordx4 v[238:239], off
	v_lshl_add_u64 v[238:239], s[46:47], 0, v[130:131]
	s_mov_b32 m0, s41
	s_nop 0
	global_load_lds_dwordx4 v[238:239], off
	s_mov_b32 m0, s51
	s_nop 0
	global_load_lds_dwordx4 v[240:241], off
	s_waitcnt vmcnt(8)
	s_waitcnt lgkmcnt(0)
	s_barrier
; #define PG8_STAGE(bufoff, gbase, voff) do { _Pragma("unroll") for (int _i = 0; _i < 2; ++_i) \
;         __builtin_amdgcn_global_load_lds((const unsigned*)((const char*)(gbase) + (voff)[_i]), (PG8_LAS unsigned*)(lds + (bufoff) + ldsw + _i * 8192), 16, 0, 0); } while (0)
; #define PG8_LDA(dst, b, h) do { _Pragma("unroll") for (int m = 0; m < 4; ++m) _Pragma("unroll") for (int k = 0; k < 2; ++k) dst[m][k] = *(const PG8_LAS bf16x8*)(lds + PG8_SA(b, h) + aoff + m * 2048 + k * 1024); } while (0)
; #define PG8_LDB(dst, b, h) do { _Pragma("unroll") for (int n = 0; n < 2; ++n) _Pragma("unroll") for (int k = 0; k < 2; ++k) dst[n][k] = *(const PG8_LAS bf16x8*)(lds + PG8_SB(b, h) + boff + n * 2048 + k * 1024); } while (0)
; #define PG8_MMA(ai, bj, At, Bt) do { __builtin_amdgcn_s_setprio(1); _Pragma("unroll") for (int m = 0; m < 4; ++m) _Pragma("unroll") for (int n = 0; n < 2; ++n) _Pragma("unroll") for (int k = 0; k < 2; ++k) \
;         acc[ai][bj][m][n] = __builtin_amdgcn_mfma_f32_16x16x32_bf16(Bt[n][k], At[m][k], acc[ai][bj][m][n], 0, 0, 0); __builtin_amdgcn_s_setprio(0); } while (0)
; #define PG8_WAIT_V(n) asm volatile("s_waitcnt vmcnt(" #n ")" ::: "memory")
; #define PG8_WAIT_L(n) asm volatile("s_waitcnt lgkmcnt(" #n ")" ::: "memory")
; #define PG8_BAR __builtin_amdgcn_s_barrier()
; #define PG8_SCHED __builtin_amdgcn_sched_barrier(0)
; template <class Epi, class Sched, bool ALIGN_EPI = false, bool SP2 = false>
; __device__ __forceinline__ void gemm_phase(PG8_LAS unsigned char* lds, const Gemm g, const Sched& S, const Epi& E) {
;     ...
;             PG8_WAIT_V(8); PG8_WAIT_L(0); PG8_BAR; PG8_MMA(1, 0, At, B0); PG8_MMA(1, 1, At, B1); PG8_BAR; PG8_SCHED;
;             PG8_LDB(B0, 1, 0); PG8_LDB(B1, 1, 1); PG8_SCHED; PG8_LDA(At, 1, 0); PG8_STAGE(PG8_SA(0, 1), a2 + hstep, voffA);
;             PG8_WAIT_V(8); PG8_WAIT_L(0); PG8_BAR; PG8_MMA(0, 0, At, B0); PG8_MMA(0, 1, At, B1); PG8_BAR; PG8_SCHED;
	s_setprio 1
	s_waitcnt lgkmcnt(0)
	v_mfma_f32_16x16x32_bf16 v[62:65], v[152:155], v[202:205], 0
	v_mfma_f32_16x16x32_bf16 v[58:61], v[160:163], v[202:205], 0
	v_mfma_f32_16x16x32_bf16 v[50:53], v[152:155], v[210:213], 0
	v_mfma_f32_16x16x32_bf16 v[46:49], v[160:163], v[210:213], 0
	v_mfma_f32_16x16x32_bf16 v[34:37], v[152:155], v[218:221], 0
	v_mfma_f32_16x16x32_bf16 v[30:33], v[160:163], v[218:221], 0
	v_mfma_f32_16x16x32_bf16 v[18:21], v[152:155], v[226:229], 0
	v_mfma_f32_16x16x32_bf16 v[14:17], v[160:163], v[226:229], 0
	v_mfma_f32_16x16x32_bf16 v[62:65], v[156:159], v[206:209], v[62:65]
	v_mfma_f32_16x16x32_bf16 v[58:61], v[182:185], v[206:209], v[58:61]
	v_mfma_f32_16x16x32_bf16 v[50:53], v[156:159], v[214:217], v[50:53]
	v_mfma_f32_16x16x32_bf16 v[46:49], v[182:185], v[214:217], v[46:49]
	v_mfma_f32_16x16x32_bf16 v[34:37], v[156:159], v[222:225], v[34:37]
	v_mfma_f32_16x16x32_bf16 v[30:33], v[182:185], v[222:225], v[30:33]
	v_mfma_f32_16x16x32_bf16 v[18:21], v[156:159], v[230:233], v[18:21]
	v_mfma_f32_16x16x32_bf16 v[14:17], v[182:185], v[230:233], v[14:17]
	s_setprio 0
	s_setprio 1
	v_mfma_f32_16x16x32_bf16 v[54:57], v[186:189], v[202:205], 0
	v_mfma_f32_16x16x32_bf16 v[42:45], v[194:197], v[202:205], 0
	v_mfma_f32_16x16x32_bf16 v[38:41], v[186:189], v[210:213], 0
	v_mfma_f32_16x16x32_bf16 v[26:29], v[194:197], v[210:213], 0
	v_mfma_f32_16x16x32_bf16 v[22:25], v[186:189], v[218:221], 0
	v_mfma_f32_16x16x32_bf16 v[10:13], v[194:197], v[218:221], 0
	v_mfma_f32_16x16x32_bf16 v[6:9], v[186:189], v[226:229], 0
	v_mfma_f32_16x16x32_bf16 v[2:5], v[194:197], v[226:229], 0
	v_mfma_f32_16x16x32_bf16 v[54:57], v[190:193], v[206:209], v[54:57]
	v_mfma_f32_16x16x32_bf16 v[42:45], v[198:201], v[206:209], v[42:45]
	v_mfma_f32_16x16x32_bf16 v[38:41], v[190:193], v[214:217], v[38:41]
	v_mfma_f32_16x16x32_bf16 v[26:29], v[198:201], v[214:217], v[26:29]
	v_mfma_f32_16x16x32_bf16 v[22:25], v[190:193], v[222:225], v[22:25]
	v_mfma_f32_16x16x32_bf16 v[10:13], v[198:201], v[222:225], v[10:13]
	v_mfma_f32_16x16x32_bf16 v[6:9], v[190:193], v[230:233], v[6:9]
	v_mfma_f32_16x16x32_bf16 v[2:5], v[198:201], v[230:233], v[2:5]
	s_setprio 0
	s_barrier
	s_add_i32 s81, 0, 0x18000
	v_add_u32_e32 v138, s81, v172
	s_add_i32 s82, 0, 0x1c000
	ds_read_b128 v[152:155], v138
	ds_read_b128 v[156:159], v138 offset:1024
	ds_read_b128 v[160:163], v138 offset:2048
	ds_read_b128 v[182:185], v138 offset:3072
	v_add_u32_e32 v138, s82, v172
	ds_read_b128 v[186:189], v138
	ds_read_b128 v[190:193], v138 offset:1024
	ds_read_b128 v[194:197], v138 offset:2048
	ds_read_b128 v[198:201], v138 offset:3072
	s_add_u32 s46, s46, 0x40000
	s_addc_u32 s47, s47, 0
	s_mov_b32 m0, s52
	v_lshl_add_u64 v[242:243], s[46:47], 0, v[130:131]
	ds_read_b128 v[202:205], v178 offset:32768
	ds_read_b128 v[206:209], v178 offset:33792
	ds_read_b128 v[210:213], v178 offset:34816
	ds_read_b128 v[214:217], v178 offset:35840
	ds_read_b128 v[218:221], v178 offset:36864
	ds_read_b128 v[222:225], v178 offset:37888
	ds_read_b128 v[226:229], v178 offset:38912
	ds_read_b128 v[230:233], v178 offset:39936
	global_load_lds_dwordx4 v[242:243], off
	v_lshl_add_u64 v[242:243], s[46:47], 0, v[134:135]
	s_mov_b32 m0, s53
	s_nop 0
	global_load_lds_dwordx4 v[242:243], off
	s_waitcnt vmcnt(8)
	s_waitcnt lgkmcnt(0)
	s_barrier
	s_setprio 1
	s_waitcnt lgkmcnt(0)
	v_mfma_f32_16x16x32_bf16 v[126:129], v[152:155], v[202:205], v[126:129]
	v_mfma_f32_16x16x32_bf16 v[122:125], v[160:163], v[202:205], v[122:125]
	v_mfma_f32_16x16x32_bf16 v[114:117], v[152:155], v[210:213], v[114:117]
	v_mfma_f32_16x16x32_bf16 v[110:113], v[160:163], v[210:213], v[110:113]
	v_mfma_f32_16x16x32_bf16 v[98:101], v[152:155], v[218:221], v[98:101]
	v_mfma_f32_16x16x32_bf16 v[94:97], v[160:163], v[218:221], v[94:97]
	v_mfma_f32_16x16x32_bf16 v[82:85], v[152:155], v[226:229], v[82:85]
	v_mfma_f32_16x16x32_bf16 v[78:81], v[160:163], v[226:229], v[78:81]
	v_mfma_f32_16x16x32_bf16 v[126:129], v[156:159], v[206:209], v[126:129]
	v_mfma_f32_16x16x32_bf16 v[122:125], v[182:185], v[206:209], v[122:125]
	v_mfma_f32_16x16x32_bf16 v[114:117], v[156:159], v[214:217], v[114:117]
	v_mfma_f32_16x16x32_bf16 v[110:113], v[182:185], v[214:217], v[110:113]
	v_mfma_f32_16x16x32_bf16 v[98:101], v[156:159], v[222:225], v[98:101]
	v_mfma_f32_16x16x32_bf16 v[94:97], v[182:185], v[222:225], v[94:97]
	v_mfma_f32_16x16x32_bf16 v[82:85], v[156:159], v[230:233], v[82:85]
	v_mfma_f32_16x16x32_bf16 v[78:81], v[182:185], v[230:233], v[78:81]
	s_setprio 0
	s_setprio 1
	v_mfma_f32_16x16x32_bf16 v[118:121], v[186:189], v[202:205], v[118:121]
	v_mfma_f32_16x16x32_bf16 v[106:109], v[194:197], v[202:205], v[106:109]
	v_mfma_f32_16x16x32_bf16 v[102:105], v[186:189], v[210:213], v[102:105]
	v_mfma_f32_16x16x32_bf16 v[90:93], v[194:197], v[210:213], v[90:93]
	v_mfma_f32_16x16x32_bf16 v[86:89], v[186:189], v[218:221], v[86:89]
	v_mfma_f32_16x16x32_bf16 v[74:77], v[194:197], v[218:221], v[74:77]
	v_mfma_f32_16x16x32_bf16 v[70:73], v[186:189], v[226:229], v[70:73]
	v_mfma_f32_16x16x32_bf16 v[66:69], v[194:197], v[226:229], v[66:69]
	v_mfma_f32_16x16x32_bf16 v[118:121], v[190:193], v[206:209], v[118:121]
	v_mfma_f32_16x16x32_bf16 v[106:109], v[198:201], v[206:209], v[106:109]
	v_mfma_f32_16x16x32_bf16 v[102:105], v[190:193], v[214:217], v[102:105]
	v_mfma_f32_16x16x32_bf16 v[90:93], v[198:201], v[214:217], v[90:93]
	v_mfma_f32_16x16x32_bf16 v[86:89], v[190:193], v[222:225], v[86:89]
	v_mfma_f32_16x16x32_bf16 v[74:77], v[198:201], v[222:225], v[74:77]
	v_mfma_f32_16x16x32_bf16 v[70:73], v[190:193], v[230:233], v[70:73]
	v_mfma_f32_16x16x32_bf16 v[66:69], v[198:201], v[230:233], v[66:69]
	s_setprio 0
	s_barrier
; #define PG8_STAGE(bufoff, gbase, voff) do { _Pragma("unroll") for (int _i = 0; _i < 2; ++_i) \
;         __builtin_amdgcn_global_load_lds((const unsigned*)((const char*)(gbase) + (voff)[_i]), (PG8_LAS unsigned*)(lds + (bufoff) + ldsw + _i * 8192), 16, 0, 0); } while (0)
; #define PG8_LDA(dst, b, h) do { _Pragma("unroll") for (int m = 0; m < 4; ++m) _Pragma("unroll") for (int k = 0; k < 2; ++k) dst[m][k] = *(const PG8_LAS bf16x8*)(lds + PG8_SA(b, h) + aoff + m * 2048 + k * 1024); } while (0)
; #define PG8_MMA(ai, bj, At, Bt) do { __builtin_amdgcn_s_setprio(1); _Pragma("unroll") for (int m = 0; m < 4; ++m) _Pragma("unroll") for (int n = 0; n < 2; ++n) _Pragma("unroll") for (int k = 0; k < 2; ++k) \
;         acc[ai][bj][m][n] = __builtin_amdgcn_mfma_f32_16x16x32_bf16(Bt[n][k], At[m][k], acc[ai][bj][m][n], 0, 0, 0); __builtin_amdgcn_s_setprio(0); } while (0)
; #define PG8_WAIT_V(n) asm volatile("s_waitcnt vmcnt(" #n ")" ::: "memory")
; #define PG8_WAIT_L(n) asm volatile("s_waitcnt lgkmcnt(" #n ")" ::: "memory")
; #define PG8_BAR __builtin_amdgcn_s_barrier()
; #define PG8_SCHED __builtin_amdgcn_sched_barrier(0)
; template <class Epi, class Sched, bool ALIGN_EPI = false, bool SP2 = false>
; __device__ __forceinline__ void gemm_phase(PG8_LAS unsigned char* lds, const Gemm g, const Sched& S, const Epi& E) {
;     ...
;             PG8_LDA(At, 1, 1); PG8_STAGE(PG8_SB(1, 0), b3, voffB); PG8_STAGE(PG8_SB(1, 1), b3 + hstep, voffB); PG8_STAGE(PG8_SA(1, 0), a3, voffA);
;             PG8_WAIT_V(8); PG8_WAIT_L(0); PG8_BAR; PG8_MMA(1, 0, At, B0); PG8_MMA(1, 1, At, B1); PG8_BAR; PG8_SCHED;
	s_add_i32 s46, s81, s15
	v_lshl_add_u64 v[234:235], v[234:235], 0, s[20:21]
	s_mov_b32 m0, s46
	ds_read_b128 v[202:205], v178 offset:49152
	ds_read_b128 v[206:209], v178 offset:50176
	ds_read_b128 v[210:213], v178 offset:51200
	ds_read_b128 v[214:217], v178 offset:52224
	ds_read_b128 v[218:221], v178 offset:53248
	ds_read_b128 v[222:225], v178 offset:54272
	ds_read_b128 v[226:229], v178 offset:55296
	ds_read_b128 v[230:233], v178 offset:56320
	global_load_lds_dwordx4 v[234:235], off
	s_add_i32 m0, s46, 0x2000
	s_add_u32 s44, s44, 0x40080
	v_lshl_add_u64 v[234:235], v[236:237], 0, s[20:21]
	s_addc_u32 s45, s45, 0
	s_add_i32 s46, s82, s15
	global_load_lds_dwordx4 v[234:235], off
	v_lshl_add_u64 v[234:235], s[44:45], 0, v[132:133]
	s_mov_b32 m0, s46
	s_nop 0
	global_load_lds_dwordx4 v[234:235], off
	v_lshl_add_u64 v[234:235], s[44:45], 0, v[136:137]
	s_add_i32 m0, s46, 0x2000
	s_nop 0
	global_load_lds_dwordx4 v[234:235], off
	v_lshl_add_u64 v[234:235], v[238:239], 0, s[20:21]
	s_mov_b32 m0, s57
	s_nop 0
	global_load_lds_dwordx4 v[234:235], off
	v_lshl_add_u64 v[234:235], v[240:241], 0, s[20:21]
	s_mov_b32 m0, s58
	s_nop 0
	global_load_lds_dwordx4 v[234:235], off
	s_waitcnt vmcnt(8)
	s_waitcnt lgkmcnt(0)
	s_barrier
	s_setprio 1
	s_waitcnt lgkmcnt(0)
	v_mfma_f32_16x16x32_bf16 v[62:65], v[152:155], v[202:205], v[62:65]
	v_mfma_f32_16x16x32_bf16 v[58:61], v[160:163], v[202:205], v[58:61]
	v_mfma_f32_16x16x32_bf16 v[50:53], v[152:155], v[210:213], v[50:53]
	v_mfma_f32_16x16x32_bf16 v[46:49], v[160:163], v[210:213], v[46:49]
	v_mfma_f32_16x16x32_bf16 v[34:37], v[152:155], v[218:221], v[34:37]
	v_mfma_f32_16x16x32_bf16 v[30:33], v[160:163], v[218:221], v[30:33]
	v_mfma_f32_16x16x32_bf16 v[18:21], v[152:155], v[226:229], v[18:21]
	v_mfma_f32_16x16x32_bf16 v[14:17], v[160:163], v[226:229], v[14:17]
	v_mfma_f32_16x16x32_bf16 v[62:65], v[156:159], v[206:209], v[62:65]
	v_mfma_f32_16x16x32_bf16 v[58:61], v[182:185], v[206:209], v[58:61]
	v_mfma_f32_16x16x32_bf16 v[50:53], v[156:159], v[214:217], v[50:53]
	v_mfma_f32_16x16x32_bf16 v[46:49], v[182:185], v[214:217], v[46:49]
	v_mfma_f32_16x16x32_bf16 v[34:37], v[156:159], v[222:225], v[34:37]
	v_mfma_f32_16x16x32_bf16 v[30:33], v[182:185], v[222:225], v[30:33]
	v_mfma_f32_16x16x32_bf16 v[18:21], v[156:159], v[230:233], v[18:21]
	v_mfma_f32_16x16x32_bf16 v[14:17], v[182:185], v[230:233], v[14:17]
	s_setprio 0
	s_setprio 1
	v_mfma_f32_16x16x32_bf16 v[54:57], v[186:189], v[202:205], v[54:57]
	v_mfma_f32_16x16x32_bf16 v[42:45], v[194:197], v[202:205], v[42:45]
	v_mfma_f32_16x16x32_bf16 v[38:41], v[186:189], v[210:213], v[38:41]
	v_mfma_f32_16x16x32_bf16 v[26:29], v[194:197], v[210:213], v[26:29]
	v_mfma_f32_16x16x32_bf16 v[22:25], v[186:189], v[218:221], v[22:25]
	v_mfma_f32_16x16x32_bf16 v[10:13], v[194:197], v[218:221], v[10:13]
	v_mfma_f32_16x16x32_bf16 v[6:9], v[186:189], v[226:229], v[6:9]
	v_mfma_f32_16x16x32_bf16 v[2:5], v[194:197], v[226:229], v[2:5]
	v_mfma_f32_16x16x32_bf16 v[54:57], v[190:193], v[206:209], v[54:57]
	v_mfma_f32_16x16x32_bf16 v[42:45], v[198:201], v[206:209], v[42:45]
	v_mfma_f32_16x16x32_bf16 v[38:41], v[190:193], v[214:217], v[38:41]
	v_mfma_f32_16x16x32_bf16 v[26:29], v[198:201], v[214:217], v[26:29]
	v_mfma_f32_16x16x32_bf16 v[22:25], v[190:193], v[222:225], v[22:25]
	v_mfma_f32_16x16x32_bf16 v[10:13], v[198:201], v[222:225], v[10:13]
	v_mfma_f32_16x16x32_bf16 v[6:9], v[190:193], v[230:233], v[6:9]
	v_mfma_f32_16x16x32_bf16 v[2:5], v[198:201], v[230:233], v[2:5]
	s_setprio 0
	s_barrier
	s_add_i32 s80, s80, 2
	s_add_u32 s42, s42, 0x100
	s_addc_u32 s43, s43, 0
	s_add_u32 s78, s78, 0x100
	s_addc_u32 s79, s79, 0
	s_cmp_gt_u32 s80, 13
	.p2align	6

; #define WAIT_BAR(N) asm volatile("s_waitcnt vmcnt(" #N ") lgkmcnt(0)\n\ts_barrier":::"memory")
;   #define DMA_K(t,slot) glds16(ksrc+(long)(t)*KVBLK*DM,(unsigned)__builtin_amdgcn_readfirstlane(kdst+(slot)))
;   #define DMA_V(t,slot) glds16(vsrc+(long)(t)*KVBLK*DM,(unsigned)__builtin_amdgcn_readfirstlane(vdst+(slot)))
;   #define BINIT(P0,P1,t) do{ _Pragma("unroll") for(int g_=0;g_<4;++g_){BL(P0,t,g_,0);BL(P1,t,g_,128);} _Pragma("unroll") for(int g_=0;g_<4;++g_){BS(P0,g_);BS(P1,g_);} }while(0)
;   #define CMASK(P0,P1,t) do{int jb_=(t)-(NT-4); if(jb_>=0)cmask(P0,P1,jb_,qrel,hi);}while(0)
;   #define START(P0,P1) do{ resc=false; \
;     if(THRL>=0){ const float rm=rowmax(P0,P1); if(__builtin_expect(__any(rm>(float)THRL),0)){ const float dl=__builtin_fmaxf(rm,0.f); mhat=fadd_s(mhat,dl); \
;       _Pragma("unroll") for(int r=0;r<16;++r){P0[r]=fsub_s(P0[r],dl);P1[r]=fsub_s(P1[r],dl);} } } \
;     _Pragma("unroll") for(int r=0;r<16;++r)P0[r]=__builtin_amdgcn_exp2f(P0[r]); }while(0)
;   #define ROT() do{sl_prev=sl_cur;sl_cur=sl_next;sl_next=(sl_next==(NSLOT-1)*SLOTB)?0:sl_next+SLOTB;}while(0)
;   #define CMASK(P0,P1,t) do{}while(0)
;   #define CMASK(P0,P1,t) do{int jb_=(t)-(NT-4); if(jb_>=0)cmask(P0,P1,jb_,qrel,hi);}while(0)
; template<int THRL> __device__ __forceinline__ void attn_unit(int b,int h,int qb,int j0,f32x4v brow0,f32x4v brow1,unsigned*ctr,unsigned&nxt,const AttnTensors&T_,char*shm){
;     ...
;   BINIT(pA0,pA1,0);
;   qkt(pA0,pA1,Kbase,qr,r32,hi);asm volatile("s_nop 15\n\ts_nop 7":"+v"(pA0),"+v"(pA1));CMASK(pA0,pA1,0);
;   START(pA0,pA1);
;   BINIT(pB0,pB1,1);
;   _Pragma("unroll") for(int r=0;r<16;++r)pA1[r]=__builtin_amdgcn_exp2f(pA1[r]);
;   WAIT_BAR(0);
;   DMA_K(3,0);DMA_V(1,SLOTB);
;   ROT();
;   kload8(kf,kp0+sl_cur);
;   WAIT_BAR(2);
;   s16x4 vlo[8],vhi[8]; u32x4 pw0,pw1,pw2,pw3;
.LBB0_353:
	s_cmp_lg_u32 0, -1
	s_nop 7
	v_exp_f32_e32 v98, v18
	v_exp_f32_e32 v99, v19
	v_exp_f32_e32 v100, v20
	v_exp_f32_e32 v101, v21
	v_exp_f32_e32 v102, v22
	v_exp_f32_e32 v103, v23
	v_exp_f32_e32 v104, v24
	v_exp_f32_e32 v105, v25
	v_exp_f32_e32 v106, v26
	v_exp_f32_e32 v107, v27
	v_exp_f32_e32 v108, v28
	v_exp_f32_e32 v109, v29
	v_exp_f32_e32 v110, v30
	v_exp_f32_e32 v111, v31
	v_exp_f32_e32 v112, v32
	v_exp_f32_e32 v113, v33
	ds_read_b128 v[18:21], v1 offset:256
	ds_read_b128 v[22:25], v1 offset:288
	ds_read_b128 v[26:29], v1 offset:448
	ds_read_b128 v[30:33], v1 offset:480
	ds_read_b128 v[34:37], v1 offset:384
	ds_read_b128 v[38:41], v1 offset:416
	ds_read_b128 v[42:45], v1 offset:320
	ds_read_b128 v[46:49], v1 offset:352
	s_waitcnt vmcnt(0) lgkmcnt(0)
	s_barrier
	s_cselect_b32 s42, 0, 0
	v_exp_f32_e32 v82, v2
	v_exp_f32_e32 v83, v3
	v_lshl_add_u64 v[2:3], v[226:227], 0, s[22:23]
	s_mov_b32 s9, m0
	s_mov_b32 m0, s67
	s_nop 0
	global_load_lds_dwordx4 v[2:3], off
	s_mov_b32 m0, s9
	s_add_i32 s12, s42, s12
	v_lshl_add_u64 v[2:3], v[228:229], 0, s[16:17]
	s_add_i32 s12, s12, 0x8000
	s_mov_b32 s42, m0
	s_mov_b32 m0, s12
	s_nop 0
	global_load_lds_dwordx4 v[2:3], off
	s_mov_b32 m0, s42
	ds_read_b128 v[174:177], v207 offset:8192
	ds_read_b128 v[170:173], v207 offset:8704
	ds_read_b128 v[166:169], v207 offset:10240
	ds_read_b128 v[162:165], v207 offset:10752
	ds_read_b128 v[158:161], v207 offset:12288
	ds_read_b128 v[154:157], v207 offset:12800
	ds_read_b128 v[150:153], v207 offset:14336
	ds_read_b128 v[146:149], v207 offset:14848
	v_exp_f32_e32 v84, v4
	v_exp_f32_e32 v85, v5
	v_exp_f32_e32 v86, v6
	v_exp_f32_e32 v87, v7
	v_exp_f32_e32 v88, v8
	v_exp_f32_e32 v89, v9
	v_exp_f32_e32 v90, v10
	v_exp_f32_e32 v91, v11
	v_exp_f32_e32 v92, v12
	v_exp_f32_e32 v93, v13
	v_exp_f32_e32 v94, v14
	v_exp_f32_e32 v95, v15
	v_exp_f32_e32 v96, v16
	v_exp_f32_e32 v97, v17
	s_waitcnt vmcnt(2) lgkmcnt(0)
	s_barrier
	s_waitcnt lgkmcnt(12)
	v_sub_f32_e32 v65, v33, v230
	v_sub_f32_e32 v64, v32, v230
	v_sub_f32_e32 v63, v31, v230
	v_sub_f32_e32 v62, v30, v230
	v_sub_f32_e32 v61, v29, v230
	v_sub_f32_e32 v60, v28, v230
	v_sub_f32_e32 v59, v27, v230
	v_sub_f32_e32 v58, v26, v230
	s_waitcnt lgkmcnt(10)
	v_sub_f32_e32 v57, v41, v230
	v_sub_f32_e32 v56, v40, v230
	v_sub_f32_e32 v55, v39, v230
	v_sub_f32_e32 v54, v38, v230
	v_sub_f32_e32 v53, v37, v230
	v_sub_f32_e32 v52, v36, v230
	v_sub_f32_e32 v51, v35, v230
	v_sub_f32_e32 v50, v34, v230
	s_waitcnt lgkmcnt(8)
	v_sub_f32_e32 v81, v49, v230
	v_sub_f32_e32 v80, v48, v230
	v_sub_f32_e32 v79, v47, v230
	v_sub_f32_e32 v78, v46, v230
	v_sub_f32_e32 v77, v45, v230
	v_sub_f32_e32 v76, v44, v230
	v_sub_f32_e32 v75, v43, v230
	v_sub_f32_e32 v74, v42, v230
	v_sub_f32_e32 v73, v25, v230
	v_sub_f32_e32 v72, v24, v230
	v_sub_f32_e32 v71, v23, v230
	v_sub_f32_e32 v70, v22, v230
	v_sub_f32_e32 v69, v21, v230
	v_sub_f32_e32 v68, v20, v230
	v_sub_f32_e32 v67, v19, v230
	v_sub_f32_e32 v66, v18, v230
	s_mov_b32 s9, 0
	s_cmp_lt_i32 s69, 7
	s_mov_b32 s43, 0
	s_cbranch_scc1 .LBB0_369
	v_mov_b32_e32 v34, 0
	v_add_u32_e32 v1, s7, v203
	v_lshl_add_u64 v[178:179], v[228:229], 0, s[22:23]
	v_lshl_add_u64 v[180:181], v[226:227], 0, s[26:27]
	s_movk_i32 s71, 0x4000
	s_movk_i32 s70, 0x2000
	s_mov_b32 s45, 6
	v_mov_b32_e32 v2, 0
	v_mov_b32_e32 v3, v34
	v_mov_b32_e32 v4, v34
	v_mov_b32_e32 v5, v34
	v_mov_b32_e32 v6, v34
	v_mov_b32_e32 v7, v34
	v_mov_b32_e32 v8, v34
	v_mov_b32_e32 v9, v34
	v_mov_b32_e32 v10, v34
	v_mov_b32_e32 v11, v34
	v_mov_b32_e32 v12, v34
	v_mov_b32_e32 v13, v34
	v_mov_b32_e32 v14, v34
	v_mov_b32_e32 v15, v34
	v_mov_b32_e32 v16, v34
	v_mov_b32_e32 v17, v34
	v_mov_b32_e32 v18, 0
	v_mov_b32_e32 v19, v34
	v_mov_b32_e32 v20, v34
	v_mov_b32_e32 v21, v34
	v_mov_b32_e32 v22, v34
	v_mov_b32_e32 v23, v34
	v_mov_b32_e32 v24, v34
	v_mov_b32_e32 v25, v34
	v_mov_b32_e32 v26, v34
	v_mov_b32_e32 v27, v34
	v_mov_b32_e32 v28, v34
	v_mov_b32_e32 v29, v34
	v_mov_b32_e32 v30, v34
	v_mov_b32_e32 v31, v34
	v_mov_b32_e32 v32, v34
	v_mov_b32_e32 v33, v34
	.p2align	6

; #define PG8_STAGE(bufoff, gbase, voff) do { _Pragma("unroll") for (int _i = 0; _i < 2; ++_i) \
;         __builtin_amdgcn_global_load_lds((const unsigned*)((const char*)(gbase) + (voff)[_i]), (PG8_LAS unsigned*)(lds + (bufoff) + ldsw + _i * 8192), 16, 0, 0); } while (0)
; #define PG8_LDA(dst, b, h) do { _Pragma("unroll") for (int m = 0; m < 4; ++m) _Pragma("unroll") for (int k = 0; k < 2; ++k) dst[m][k] = *(const PG8_LAS bf16x8*)(lds + PG8_SA(b, h) + aoff + m * 2048 + k * 1024); } while (0)
; #define PG8_LDB(dst, b, h) do { _Pragma("unroll") for (int n = 0; n < 2; ++n) _Pragma("unroll") for (int k = 0; k < 2; ++k) dst[n][k] = *(const PG8_LAS bf16x8*)(lds + PG8_SB(b, h) + boff + n * 2048 + k * 1024); } while (0)
; #define PG8_WAIT_V(n) asm volatile("s_waitcnt vmcnt(" #n ")" ::: "memory")
; #define PG8_WAIT_L(n) asm volatile("s_waitcnt lgkmcnt(" #n ")" ::: "memory")
; #define PG8_BAR __builtin_amdgcn_s_barrier()
; #define PG8_SCHED __builtin_amdgcn_sched_barrier(0)
; template <class Epi, class Sched, bool ALIGN_EPI = false, bool SP2 = false>
; __device__ __forceinline__ void gemm_phase(PG8_LAS unsigned char* lds, const Gemm g, const Sched& S, const Epi& E) {
;     ...
;         const char* nA = has_next ? (const char*)g.A + (size_t)nxt.pm * tstep : cA; const char* nB = has_next ? (const char*)g.Bt + (size_t)nxt.pn * tstep : cB;
;         for (int t = 0; t < nt; t += 2) {
;             if constexpr (Epi::MID) { if (t == nt / 2) E.mid(acc, cur, wr, wc, fr, fq); }
;             const bool last = (t == nt - 2);
;             const char* a1 = cA + (size_t)(t + 1) * kstep;
;             const char* a2 = last ? nA : cA + (size_t)(t + 2) * kstep; const char* b2 = last ? nB : cB + (size_t)(t + 2) * kstep;
;             const char* a3 = a2 + kstep; const char* b3 = b2 + kstep;
;             if (last && has_next) S.a_ready(nxt);
;             if constexpr (SP2) {
;             PG8_LDB(B0, 0, 0); PG8_LDB(B1, 0, 1); PG8_SCHED; PG8_LDA(At, 0, 0); PG8_STAGE(PG8_SA(1, 1), a1 + hstep, voffA);
;             PG8_WAIT_V(8); PG8_WAIT_L(0); PG8_BAR; PG8_MMA(0, 0, At, B0); PG8_MMA(0, 1, At, B1); PG8_BAR; PG8_SCHED;
;             PG8_LDA(At, 0, 1); PG8_STAGE(PG8_SB(0, 0), b2, voffB); PG8_STAGE(PG8_SB(0, 1), b2 + hstep, voffB); PG8_STAGE(PG8_SA(0, 0), a2, voffA);
;             PG8_WAIT_V(8); PG8_WAIT_L(0); PG8_BAR; PG8_MMA(1, 0, At, B0); PG8_MMA(1, 1, At, B1); PG8_BAR; PG8_SCHED;
.LBB0_506:
	s_ashr_i32 s23, s22, 31
	s_lshl_b64 s[26:27], s[22:23], 19
	s_add_u32 s26, s43, s26
	s_addc_u32 s27, s44, s27
	s_and_b64 s[28:29], s[4:5], exec
	s_cselect_b32 s23, s27, s31
	s_cselect_b32 s56, s26, s30
	s_ashr_i32 s21, s20, 31
	s_lshl_b64 s[28:29], s[20:21], 19
	s_add_u32 s28, s41, s28
	s_addc_u32 s29, s42, s29
	s_and_b64 s[38:39], s[4:5], exec
	s_cselect_b32 s21, s29, s37
	s_cselect_b32 s57, s28, s36
	s_lshl_b32 s34, s34, 18
	s_lshl_b32 s35, s35, 8
	s_add_i32 s34, s34, s35
	s_add_u32 s58, s36, 0x100
	v_add_u32_e32 v168, s34, v174
	v_lshl_add_u64 v[170:171], s[30:31], 0, v[160:161]
	v_lshl_add_u64 v[172:173], s[30:31], 0, v[162:163]
	s_addc_u32 s59, s37, 0
	s_mov_b32 s60, -2
	s_mov_b64 s[34:35], 0
	v_add_u32_e32 v2, s54, v1
	ds_read_b128 v[134:137], v2
	ds_read_b128 v[138:141], v2 offset:1024
	ds_read_b128 v[142:145], v2 offset:2048
	ds_read_b128 v[146:149], v2 offset:3072
	v_add_u32_e32 v2, s55, v1
	s_add_u32 s36, s30, s34
	ds_read_b128 v[176:179], v2
	ds_read_b128 v[180:183], v2 offset:1024
	ds_read_b128 v[184:187], v2 offset:2048
	ds_read_b128 v[188:191], v2 offset:3072
	s_addc_u32 s37, s31, s35
	s_add_u32 s36, s36, 0x100
	s_addc_u32 s37, s37, 0
	s_add_u32 s61, s58, s34
	s_addc_u32 s62, s59, s35
	s_cmpk_eq_i32 s34, 0x700
	s_cselect_b32 s39, s23, s37
	s_cselect_b32 s38, s56, s36
	s_cselect_b32 s37, s21, s62
	s_cselect_b32 s36, s57, s61
	v_lshl_add_u64 v[4:5], v[170:171], 0, s[34:35]
	s_add_i32 m0, s46, 0xc000
	ds_read_b128 v[192:195], v175
	ds_read_b128 v[196:199], v175 offset:1024
	ds_read_b128 v[200:203], v175 offset:2048
	ds_read_b128 v[204:207], v175 offset:3072
	ds_read_b128 v[208:211], v175 offset:4096
	ds_read_b128 v[212:215], v175 offset:5120
	ds_read_b128 v[216:219], v175 offset:6144
	ds_read_b128 v[220:223], v175 offset:7168
	global_load_lds_dwordx4 v[4:5], off
	v_lshl_add_u64 v[4:5], v[172:173], 0, s[34:35]
	s_add_i32 m0, s46, 0xe000
	s_nop 0
	global_load_lds_dwordx4 v[4:5], off
	s_waitcnt vmcnt(8)
	s_waitcnt lgkmcnt(0)
	s_barrier
	s_setprio 1
	s_waitcnt lgkmcnt(0)
	v_mfma_f32_16x16x32_bf16 v[130:133], v[134:137], v[192:195], 0
	v_mfma_f32_16x16x32_bf16 v[126:129], v[142:145], v[192:195], 0
	v_mfma_f32_16x16x32_bf16 v[114:117], v[134:137], v[200:203], 0
	v_mfma_f32_16x16x32_bf16 v[110:113], v[142:145], v[200:203], 0
	v_mfma_f32_16x16x32_bf16 v[98:101], v[134:137], v[208:211], 0
	v_mfma_f32_16x16x32_bf16 v[94:97], v[142:145], v[208:211], 0
	v_mfma_f32_16x16x32_bf16 v[82:85], v[134:137], v[216:219], 0
	v_mfma_f32_16x16x32_bf16 v[78:81], v[142:145], v[216:219], 0
	v_mfma_f32_16x16x32_bf16 v[130:133], v[138:141], v[196:199], v[130:133]
	v_mfma_f32_16x16x32_bf16 v[126:129], v[146:149], v[196:199], v[126:129]
	v_mfma_f32_16x16x32_bf16 v[114:117], v[138:141], v[204:207], v[114:117]
	v_mfma_f32_16x16x32_bf16 v[110:113], v[146:149], v[204:207], v[110:113]
	v_mfma_f32_16x16x32_bf16 v[98:101], v[138:141], v[212:215], v[98:101]
	v_mfma_f32_16x16x32_bf16 v[94:97], v[146:149], v[212:215], v[94:97]
	v_mfma_f32_16x16x32_bf16 v[82:85], v[138:141], v[220:223], v[82:85]
	v_mfma_f32_16x16x32_bf16 v[78:81], v[146:149], v[220:223], v[78:81]
	s_setprio 0
	s_setprio 1
	v_mfma_f32_16x16x32_bf16 v[122:125], v[176:179], v[192:195], 0
	v_mfma_f32_16x16x32_bf16 v[118:121], v[184:187], v[192:195], 0
	v_mfma_f32_16x16x32_bf16 v[106:109], v[176:179], v[200:203], 0
	v_mfma_f32_16x16x32_bf16 v[102:105], v[184:187], v[200:203], 0
	v_mfma_f32_16x16x32_bf16 v[90:93], v[176:179], v[208:211], 0
	v_mfma_f32_16x16x32_bf16 v[86:89], v[184:187], v[208:211], 0
	v_mfma_f32_16x16x32_bf16 v[74:77], v[176:179], v[216:219], 0
	v_mfma_f32_16x16x32_bf16 v[70:73], v[184:187], v[216:219], 0
	v_mfma_f32_16x16x32_bf16 v[122:125], v[180:183], v[196:199], v[122:125]
	v_mfma_f32_16x16x32_bf16 v[118:121], v[188:191], v[196:199], v[118:121]
	v_mfma_f32_16x16x32_bf16 v[106:109], v[180:183], v[204:207], v[106:109]
	v_mfma_f32_16x16x32_bf16 v[102:105], v[188:191], v[204:207], v[102:105]
	v_mfma_f32_16x16x32_bf16 v[90:93], v[180:183], v[212:215], v[90:93]
	v_mfma_f32_16x16x32_bf16 v[86:89], v[188:191], v[212:215], v[86:89]
	v_mfma_f32_16x16x32_bf16 v[74:77], v[180:183], v[220:223], v[74:77]
	v_mfma_f32_16x16x32_bf16 v[70:73], v[188:191], v[220:223], v[70:73]
	s_setprio 0
	s_barrier
	s_add_i32 s61, s54, s45
	v_lshl_add_u64 v[150:151], s[36:37], 0, v[154:155]
	s_mov_b32 m0, s61
	ds_read_b128 v[192:195], v175 offset:16384
	ds_read_b128 v[196:199], v175 offset:17408
	ds_read_b128 v[200:203], v175 offset:18432
	ds_read_b128 v[204:207], v175 offset:19456
	ds_read_b128 v[208:211], v175 offset:20480
	ds_read_b128 v[212:215], v175 offset:21504
	ds_read_b128 v[216:219], v175 offset:22528
	ds_read_b128 v[220:223], v175 offset:23552
	global_load_lds_dwordx4 v[150:151], off
	s_add_i32 m0, s61, 0x2000
	s_add_u32 s62, s36, 0x40000
	v_lshl_add_u64 v[224:225], s[36:37], 0, v[158:159]
	s_addc_u32 s63, s37, 0
	s_add_i32 s61, s55, s45
	global_load_lds_dwordx4 v[224:225], off
	v_lshl_add_u64 v[4:5], s[62:63], 0, v[154:155]
	s_mov_b32 m0, s61
	v_lshl_add_u64 v[226:227], s[38:39], 0, v[152:153]
	global_load_lds_dwordx4 v[4:5], off
	v_lshl_add_u64 v[4:5], s[62:63], 0, v[158:159]
	s_add_i32 m0, s61, 0x2000
	v_lshl_add_u64 v[228:229], s[38:39], 0, v[156:157]
	global_load_lds_dwordx4 v[4:5], off
	s_mov_b32 m0, s46
	s_nop 0
	global_load_lds_dwordx4 v[226:227], off
	s_mov_b32 m0, s47
	s_nop 0
	global_load_lds_dwordx4 v[228:229], off
	s_waitcnt vmcnt(8)
	s_waitcnt lgkmcnt(0)
	s_barrier
; #define PG8_STAGE(bufoff, gbase, voff) do { _Pragma("unroll") for (int _i = 0; _i < 2; ++_i) \
;         __builtin_amdgcn_global_load_lds((const unsigned*)((const char*)(gbase) + (voff)[_i]), (PG8_LAS unsigned*)(lds + (bufoff) + ldsw + _i * 8192), 16, 0, 0); } while (0)
; #define PG8_LDA(dst, b, h) do { _Pragma("unroll") for (int m = 0; m < 4; ++m) _Pragma("unroll") for (int k = 0; k < 2; ++k) dst[m][k] = *(const PG8_LAS bf16x8*)(lds + PG8_SA(b, h) + aoff + m * 2048 + k * 1024); } while (0)
; #define PG8_LDB(dst, b, h) do { _Pragma("unroll") for (int n = 0; n < 2; ++n) _Pragma("unroll") for (int k = 0; k < 2; ++k) dst[n][k] = *(const PG8_LAS bf16x8*)(lds + PG8_SB(b, h) + boff + n * 2048 + k * 1024); } while (0)
; #define PG8_MMA(ai, bj, At, Bt) do { __builtin_amdgcn_s_setprio(1); _Pragma("unroll") for (int m = 0; m < 4; ++m) _Pragma("unroll") for (int n = 0; n < 2; ++n) _Pragma("unroll") for (int k = 0; k < 2; ++k) \
;         acc[ai][bj][m][n] = __builtin_amdgcn_mfma_f32_16x16x32_bf16(Bt[n][k], At[m][k], acc[ai][bj][m][n], 0, 0, 0); __builtin_amdgcn_s_setprio(0); } while (0)
; #define PG8_WAIT_V(n) asm volatile("s_waitcnt vmcnt(" #n ")" ::: "memory")
; #define PG8_WAIT_L(n) asm volatile("s_waitcnt lgkmcnt(" #n ")" ::: "memory")
; #define PG8_BAR __builtin_amdgcn_s_barrier()
; #define PG8_SCHED __builtin_amdgcn_sched_barrier(0)
; template <class Epi, class Sched, bool ALIGN_EPI = false, bool SP2 = false>
; __device__ __forceinline__ void gemm_phase(PG8_LAS unsigned char* lds, const Gemm g, const Sched& S, const Epi& E) {
;     ...
;             PG8_WAIT_V(8); PG8_WAIT_L(0); PG8_BAR; PG8_MMA(1, 0, At, B0); PG8_MMA(1, 1, At, B1); PG8_BAR; PG8_SCHED;
;             PG8_LDB(B0, 1, 0); PG8_LDB(B1, 1, 1); PG8_SCHED; PG8_LDA(At, 1, 0); PG8_STAGE(PG8_SA(0, 1), a2 + hstep, voffA);
;             PG8_WAIT_V(8); PG8_WAIT_L(0); PG8_BAR; PG8_MMA(0, 0, At, B0); PG8_MMA(0, 1, At, B1); PG8_BAR; PG8_SCHED;
	s_setprio 1
	s_waitcnt lgkmcnt(0)
	v_mfma_f32_16x16x32_bf16 v[66:69], v[134:137], v[192:195], 0
	v_mfma_f32_16x16x32_bf16 v[62:65], v[142:145], v[192:195], 0
	v_mfma_f32_16x16x32_bf16 v[50:53], v[134:137], v[200:203], 0
	v_mfma_f32_16x16x32_bf16 v[46:49], v[142:145], v[200:203], 0
	v_mfma_f32_16x16x32_bf16 v[34:37], v[134:137], v[208:211], 0
	v_mfma_f32_16x16x32_bf16 v[30:33], v[142:145], v[208:211], 0
	v_mfma_f32_16x16x32_bf16 v[18:21], v[134:137], v[216:219], 0
	v_mfma_f32_16x16x32_bf16 v[14:17], v[142:145], v[216:219], 0
	v_mfma_f32_16x16x32_bf16 v[66:69], v[138:141], v[196:199], v[66:69]
	v_mfma_f32_16x16x32_bf16 v[62:65], v[146:149], v[196:199], v[62:65]
	v_mfma_f32_16x16x32_bf16 v[50:53], v[138:141], v[204:207], v[50:53]
	v_mfma_f32_16x16x32_bf16 v[46:49], v[146:149], v[204:207], v[46:49]
	v_mfma_f32_16x16x32_bf16 v[34:37], v[138:141], v[212:215], v[34:37]
	v_mfma_f32_16x16x32_bf16 v[30:33], v[146:149], v[212:215], v[30:33]
	v_mfma_f32_16x16x32_bf16 v[18:21], v[138:141], v[220:223], v[18:21]
	v_mfma_f32_16x16x32_bf16 v[14:17], v[146:149], v[220:223], v[14:17]
	s_setprio 0
	s_setprio 1
	v_mfma_f32_16x16x32_bf16 v[58:61], v[176:179], v[192:195], 0
	v_mfma_f32_16x16x32_bf16 v[54:57], v[184:187], v[192:195], 0
	v_mfma_f32_16x16x32_bf16 v[42:45], v[176:179], v[200:203], 0
	v_mfma_f32_16x16x32_bf16 v[38:41], v[184:187], v[200:203], 0
	v_mfma_f32_16x16x32_bf16 v[26:29], v[176:179], v[208:211], 0
	v_mfma_f32_16x16x32_bf16 v[22:25], v[184:187], v[208:211], 0
	v_mfma_f32_16x16x32_bf16 v[10:13], v[176:179], v[216:219], 0
	v_mfma_f32_16x16x32_bf16 v[4:7], v[184:187], v[216:219], 0
	v_mfma_f32_16x16x32_bf16 v[58:61], v[180:183], v[196:199], v[58:61]
	v_mfma_f32_16x16x32_bf16 v[54:57], v[188:191], v[196:199], v[54:57]
	v_mfma_f32_16x16x32_bf16 v[42:45], v[180:183], v[204:207], v[42:45]
	v_mfma_f32_16x16x32_bf16 v[38:41], v[188:191], v[204:207], v[38:41]
	v_mfma_f32_16x16x32_bf16 v[26:29], v[180:183], v[212:215], v[26:29]
	v_mfma_f32_16x16x32_bf16 v[22:25], v[188:191], v[212:215], v[22:25]
	v_mfma_f32_16x16x32_bf16 v[10:13], v[180:183], v[220:223], v[10:13]
	v_mfma_f32_16x16x32_bf16 v[4:7], v[188:191], v[220:223], v[4:7]
	s_setprio 0
	s_barrier
	s_add_i32 s61, 0, 0x18000
	v_add_u32_e32 v2, s61, v1
	s_add_i32 s62, 0, 0x1c000
	ds_read_b128 v[134:137], v2
	ds_read_b128 v[138:141], v2 offset:1024
	ds_read_b128 v[142:145], v2 offset:2048
	ds_read_b128 v[146:149], v2 offset:3072
	v_add_u32_e32 v2, s62, v1
	ds_read_b128 v[176:179], v2
	ds_read_b128 v[180:183], v2 offset:1024
	ds_read_b128 v[184:187], v2 offset:2048
	ds_read_b128 v[188:191], v2 offset:3072
	s_add_u32 s38, s38, 0x40000
	s_addc_u32 s39, s39, 0
	s_mov_b32 m0, s48
	v_lshl_add_u64 v[8:9], s[38:39], 0, v[152:153]
	ds_read_b128 v[192:195], v175 offset:32768
	ds_read_b128 v[196:199], v175 offset:33792
	ds_read_b128 v[200:203], v175 offset:34816
	ds_read_b128 v[204:207], v175 offset:35840
	ds_read_b128 v[208:211], v175 offset:36864
	ds_read_b128 v[212:215], v175 offset:37888
	ds_read_b128 v[216:219], v175 offset:38912
	ds_read_b128 v[220:223], v175 offset:39936
	global_load_lds_dwordx4 v[8:9], off
	v_lshl_add_u64 v[8:9], s[38:39], 0, v[156:157]
	s_mov_b32 m0, s49
	s_nop 0
	global_load_lds_dwordx4 v[8:9], off
	s_waitcnt vmcnt(8)
	s_waitcnt lgkmcnt(0)
	s_barrier
	s_setprio 1
	s_waitcnt lgkmcnt(0)
	v_mfma_f32_16x16x32_bf16 v[130:133], v[134:137], v[192:195], v[130:133]
	v_mfma_f32_16x16x32_bf16 v[126:129], v[142:145], v[192:195], v[126:129]
	v_mfma_f32_16x16x32_bf16 v[114:117], v[134:137], v[200:203], v[114:117]
	v_mfma_f32_16x16x32_bf16 v[110:113], v[142:145], v[200:203], v[110:113]
	v_mfma_f32_16x16x32_bf16 v[98:101], v[134:137], v[208:211], v[98:101]
	v_mfma_f32_16x16x32_bf16 v[94:97], v[142:145], v[208:211], v[94:97]
	v_mfma_f32_16x16x32_bf16 v[82:85], v[134:137], v[216:219], v[82:85]
	v_mfma_f32_16x16x32_bf16 v[78:81], v[142:145], v[216:219], v[78:81]
	v_mfma_f32_16x16x32_bf16 v[130:133], v[138:141], v[196:199], v[130:133]
	v_mfma_f32_16x16x32_bf16 v[126:129], v[146:149], v[196:199], v[126:129]
	v_mfma_f32_16x16x32_bf16 v[114:117], v[138:141], v[204:207], v[114:117]
	v_mfma_f32_16x16x32_bf16 v[110:113], v[146:149], v[204:207], v[110:113]
	v_mfma_f32_16x16x32_bf16 v[98:101], v[138:141], v[212:215], v[98:101]
	v_mfma_f32_16x16x32_bf16 v[94:97], v[146:149], v[212:215], v[94:97]
	v_mfma_f32_16x16x32_bf16 v[82:85], v[138:141], v[220:223], v[82:85]
	v_mfma_f32_16x16x32_bf16 v[78:81], v[146:149], v[220:223], v[78:81]
	s_setprio 0
	s_setprio 1
	v_mfma_f32_16x16x32_bf16 v[122:125], v[176:179], v[192:195], v[122:125]
	v_mfma_f32_16x16x32_bf16 v[118:121], v[184:187], v[192:195], v[118:121]
	v_mfma_f32_16x16x32_bf16 v[106:109], v[176:179], v[200:203], v[106:109]
	v_mfma_f32_16x16x32_bf16 v[102:105], v[184:187], v[200:203], v[102:105]
	v_mfma_f32_16x16x32_bf16 v[90:93], v[176:179], v[208:211], v[90:93]
	v_mfma_f32_16x16x32_bf16 v[86:89], v[184:187], v[208:211], v[86:89]
	v_mfma_f32_16x16x32_bf16 v[74:77], v[176:179], v[216:219], v[74:77]
	v_mfma_f32_16x16x32_bf16 v[70:73], v[184:187], v[216:219], v[70:73]
	v_mfma_f32_16x16x32_bf16 v[122:125], v[180:183], v[196:199], v[122:125]
	v_mfma_f32_16x16x32_bf16 v[118:121], v[188:191], v[196:199], v[118:121]
	v_mfma_f32_16x16x32_bf16 v[106:109], v[180:183], v[204:207], v[106:109]
	v_mfma_f32_16x16x32_bf16 v[102:105], v[188:191], v[204:207], v[102:105]
	v_mfma_f32_16x16x32_bf16 v[90:93], v[180:183], v[212:215], v[90:93]
	v_mfma_f32_16x16x32_bf16 v[86:89], v[188:191], v[212:215], v[86:89]
	v_mfma_f32_16x16x32_bf16 v[74:77], v[180:183], v[220:223], v[74:77]
	v_mfma_f32_16x16x32_bf16 v[70:73], v[188:191], v[220:223], v[70:73]
	s_setprio 0
	s_barrier
; #define PG8_STAGE(bufoff, gbase, voff) do { _Pragma("unroll") for (int _i = 0; _i < 2; ++_i) \
;         __builtin_amdgcn_global_load_lds((const unsigned*)((const char*)(gbase) + (voff)[_i]), (PG8_LAS unsigned*)(lds + (bufoff) + ldsw + _i * 8192), 16, 0, 0); } while (0)
; #define PG8_LDA(dst, b, h) do { _Pragma("unroll") for (int m = 0; m < 4; ++m) _Pragma("unroll") for (int k = 0; k < 2; ++k) dst[m][k] = *(const PG8_LAS bf16x8*)(lds + PG8_SA(b, h) + aoff + m * 2048 + k * 1024); } while (0)
; #define PG8_MMA(ai, bj, At, Bt) do { __builtin_amdgcn_s_setprio(1); _Pragma("unroll") for (int m = 0; m < 4; ++m) _Pragma("unroll") for (int n = 0; n < 2; ++n) _Pragma("unroll") for (int k = 0; k < 2; ++k) \
;         acc[ai][bj][m][n] = __builtin_amdgcn_mfma_f32_16x16x32_bf16(Bt[n][k], At[m][k], acc[ai][bj][m][n], 0, 0, 0); __builtin_amdgcn_s_setprio(0); } while (0)
; #define PG8_WAIT_V(n) asm volatile("s_waitcnt vmcnt(" #n ")" ::: "memory")
; #define PG8_WAIT_L(n) asm volatile("s_waitcnt lgkmcnt(" #n ")" ::: "memory")
; #define PG8_BAR __builtin_amdgcn_s_barrier()
; #define PG8_SCHED __builtin_amdgcn_sched_barrier(0)
; template <class Epi, class Sched, bool ALIGN_EPI = false, bool SP2 = false>
; __device__ __forceinline__ void gemm_phase(PG8_LAS unsigned char* lds, const Gemm g, const Sched& S, const Epi& E) {
;     ...
;             PG8_LDA(At, 1, 1); PG8_STAGE(PG8_SB(1, 0), b3, voffB); PG8_STAGE(PG8_SB(1, 1), b3 + hstep, voffB); PG8_STAGE(PG8_SA(1, 0), a3, voffA);
;             PG8_WAIT_V(8); PG8_WAIT_L(0); PG8_BAR; PG8_MMA(1, 0, At, B0); PG8_MMA(1, 1, At, B1); PG8_BAR; PG8_SCHED;
	s_add_i32 s38, s61, s45
	v_lshl_add_u64 v[8:9], v[150:151], 0, s[12:13]
	s_mov_b32 m0, s38
	ds_read_b128 v[192:195], v175 offset:49152
	ds_read_b128 v[196:199], v175 offset:50176
	ds_read_b128 v[200:203], v175 offset:51200
	ds_read_b128 v[204:207], v175 offset:52224
	ds_read_b128 v[208:211], v175 offset:53248
	ds_read_b128 v[212:215], v175 offset:54272
	ds_read_b128 v[216:219], v175 offset:55296
	ds_read_b128 v[220:223], v175 offset:56320
	global_load_lds_dwordx4 v[8:9], off
	s_add_i32 m0, s38, 0x2000
	s_add_u32 s36, s36, 0x40080
	v_lshl_add_u64 v[8:9], v[224:225], 0, s[12:13]
	s_addc_u32 s37, s37, 0
	s_add_i32 s38, s62, s45
	global_load_lds_dwordx4 v[8:9], off
	v_lshl_add_u64 v[8:9], s[36:37], 0, v[154:155]
	s_mov_b32 m0, s38
	s_nop 0
	global_load_lds_dwordx4 v[8:9], off
	v_lshl_add_u64 v[8:9], s[36:37], 0, v[158:159]
	s_add_i32 m0, s38, 0x2000
	s_nop 0
	global_load_lds_dwordx4 v[8:9], off
	v_lshl_add_u64 v[8:9], v[226:227], 0, s[12:13]
	s_mov_b32 m0, s51
	s_nop 0
	global_load_lds_dwordx4 v[8:9], off
	v_lshl_add_u64 v[8:9], v[228:229], 0, s[12:13]
	s_mov_b32 m0, s52
	s_nop 0
	global_load_lds_dwordx4 v[8:9], off
	s_waitcnt vmcnt(8)
	s_waitcnt lgkmcnt(0)
	s_barrier
	s_setprio 1
	s_waitcnt lgkmcnt(0)
	v_mfma_f32_16x16x32_bf16 v[66:69], v[134:137], v[192:195], v[66:69]
	v_mfma_f32_16x16x32_bf16 v[62:65], v[142:145], v[192:195], v[62:65]
	v_mfma_f32_16x16x32_bf16 v[50:53], v[134:137], v[200:203], v[50:53]
	v_mfma_f32_16x16x32_bf16 v[46:49], v[142:145], v[200:203], v[46:49]
	v_mfma_f32_16x16x32_bf16 v[34:37], v[134:137], v[208:211], v[34:37]
	v_mfma_f32_16x16x32_bf16 v[30:33], v[142:145], v[208:211], v[30:33]
	v_mfma_f32_16x16x32_bf16 v[18:21], v[134:137], v[216:219], v[18:21]
	v_mfma_f32_16x16x32_bf16 v[14:17], v[142:145], v[216:219], v[14:17]
	v_mfma_f32_16x16x32_bf16 v[66:69], v[138:141], v[196:199], v[66:69]
	v_mfma_f32_16x16x32_bf16 v[62:65], v[146:149], v[196:199], v[62:65]
	v_mfma_f32_16x16x32_bf16 v[50:53], v[138:141], v[204:207], v[50:53]
	v_mfma_f32_16x16x32_bf16 v[46:49], v[146:149], v[204:207], v[46:49]
	v_mfma_f32_16x16x32_bf16 v[34:37], v[138:141], v[212:215], v[34:37]
	v_mfma_f32_16x16x32_bf16 v[30:33], v[146:149], v[212:215], v[30:33]
	v_mfma_f32_16x16x32_bf16 v[18:21], v[138:141], v[220:223], v[18:21]
	v_mfma_f32_16x16x32_bf16 v[14:17], v[146:149], v[220:223], v[14:17]
	s_setprio 0
	s_setprio 1
	v_mfma_f32_16x16x32_bf16 v[58:61], v[176:179], v[192:195], v[58:61]
	v_mfma_f32_16x16x32_bf16 v[54:57], v[184:187], v[192:195], v[54:57]
	v_mfma_f32_16x16x32_bf16 v[42:45], v[176:179], v[200:203], v[42:45]
	v_mfma_f32_16x16x32_bf16 v[38:41], v[184:187], v[200:203], v[38:41]
	v_mfma_f32_16x16x32_bf16 v[26:29], v[176:179], v[208:211], v[26:29]
	v_mfma_f32_16x16x32_bf16 v[22:25], v[184:187], v[208:211], v[22:25]
	v_mfma_f32_16x16x32_bf16 v[8:11], v[176:179], v[216:219], v[10:13]
	v_mfma_f32_16x16x32_bf16 v[4:7], v[184:187], v[216:219], v[4:7]
	v_mfma_f32_16x16x32_bf16 v[58:61], v[180:183], v[196:199], v[58:61]
	v_mfma_f32_16x16x32_bf16 v[54:57], v[188:191], v[196:199], v[54:57]
	v_mfma_f32_16x16x32_bf16 v[42:45], v[180:183], v[204:207], v[42:45]
	v_mfma_f32_16x16x32_bf16 v[38:41], v[188:191], v[204:207], v[38:41]
	v_mfma_f32_16x16x32_bf16 v[26:29], v[180:183], v[212:215], v[26:29]
	v_mfma_f32_16x16x32_bf16 v[22:25], v[188:191], v[212:215], v[22:25]
	v_mfma_f32_16x16x32_bf16 v[10:13], v[180:183], v[220:223], v[8:11]
	v_mfma_f32_16x16x32_bf16 v[6:9], v[188:191], v[220:223], v[4:7]
	s_setprio 0
	s_barrier
	s_add_i32 s60, s60, 2
	s_add_u32 s34, s34, 0x100
	s_addc_u32 s35, s35, 0
	s_cmp_gt_u32 s60, 13
	s_cbranch_scc1 .LBB0_510
	s_branch .LBB0_508
	.p2align	6

; #define PG8_STAGE(bufoff, gbase, voff) do { _Pragma("unroll") for (int _i = 0; _i < 2; ++_i) \
;         __builtin_amdgcn_global_load_lds((const unsigned*)((const char*)(gbase) + (voff)[_i]), (PG8_LAS unsigned*)(lds + (bufoff) + ldsw + _i * 8192), 16, 0, 0); } while (0)
; #define PG8_LDA(dst, b, h) do { _Pragma("unroll") for (int m = 0; m < 4; ++m) _Pragma("unroll") for (int k = 0; k < 2; ++k) dst[m][k] = *(const PG8_LAS bf16x8*)(lds + PG8_SA(b, h) + aoff + m * 2048 + k * 1024); } while (0)
; #define PG8_LDB(dst, b, h) do { _Pragma("unroll") for (int n = 0; n < 2; ++n) _Pragma("unroll") for (int k = 0; k < 2; ++k) dst[n][k] = *(const PG8_LAS bf16x8*)(lds + PG8_SB(b, h) + boff + n * 2048 + k * 1024); } while (0)
; #define PG8_WAIT_V(n) asm volatile("s_waitcnt vmcnt(" #n ")" ::: "memory")
; #define PG8_WAIT_L(n) asm volatile("s_waitcnt lgkmcnt(" #n ")" ::: "memory")
; #define PG8_BAR __builtin_amdgcn_s_barrier()
; template <class Epi, class Sched, bool ALIGN_EPI = false, bool SP2 = false>
; __device__ __forceinline__ void gemm_phase(PG8_LAS unsigned char* lds, const Gemm g, const Sched& S, const Epi& E) {
;     ...
;         const bool has_next = S.next(ui + 1, nxt);
;         const char* nA = has_next ? (const char*)g.A + (size_t)nxt.pm * tstep : cA; const char* nB = has_next ? (const char*)g.Bt + (size_t)nxt.pn * tstep : cB;
;         for (int t = 0; t < nt; t += 2) {
;             if constexpr (Epi::MID) { if (t == nt / 2) E.mid(acc, cur, wr, wc, fr, fq); }
;             const bool last = (t == nt - 2);
;             const char* a1 = cA + (size_t)(t + 1) * kstep;
;             const char* a2 = last ? nA : cA + (size_t)(t + 2) * kstep; const char* b2 = last ? nB : cB + (size_t)(t + 2) * kstep;
;             const char* a3 = a2 + kstep; const char* b3 = b2 + kstep;
;             if (last && has_next) S.a_ready(nxt);
;             if constexpr (SP2) {
;             PG8_LDB(B0, 0, 0); PG8_LDB(B1, 0, 1); PG8_SCHED; PG8_LDA(At, 0, 0); PG8_STAGE(PG8_SA(1, 1), a1 + hstep, voffA);
;             PG8_WAIT_V(8); PG8_WAIT_L(0); PG8_BAR; PG8_MMA(0, 0, At, B0); PG8_MMA(0, 1, At, B1); PG8_BAR; PG8_SCHED;
;             PG8_LDA(At, 0, 1); PG8_STAGE(PG8_SB(0, 0), b2, voffB); PG8_STAGE(PG8_SB(0, 1), b2 + hstep, voffB); PG8_STAGE(PG8_SA(0, 0), a2, voffA);
;             PG8_WAIT_V(8); PG8_WAIT_L(0); PG8_BAR; PG8_MMA(1, 0, At, B0); PG8_MMA(1, 1, At, B1); PG8_BAR; PG8_SCHED;
.LBB0_584:
	s_ashr_i32 s25, s24, 31
	s_lshl_b64 s[26:27], s[24:25], 19
	s_add_u32 s26, s42, s26
	s_addc_u32 s27, s43, s27
	s_and_b64 s[28:29], s[0:1], exec
	s_cselect_b32 s25, s27, s35
	s_cselect_b32 s31, s26, s34
	s_ashr_i32 s23, s22, 31
	s_lshl_b64 s[28:29], s[22:23], 19
	s_add_u32 s28, s40, s28
	s_addc_u32 s29, s41, s29
	s_and_b64 s[38:39], s[0:1], exec
	s_cselect_b32 s23, s29, s37
	s_cselect_b32 s62, s28, s36
	s_add_u32 s34, s34, 0x40080
	s_addc_u32 s35, s35, 0
	s_add_u32 s63, s36, 0x100
	s_addc_u32 s64, s37, 0
	s_mov_b32 s65, -2
	ds_read_b128 v[128:131], v164
	ds_read_b128 v[132:135], v164 offset:1024
	ds_read_b128 v[136:139], v164 offset:2048
	ds_read_b128 v[140:143], v164 offset:3072
	ds_read_b128 v[158:161], v165
	ds_read_b128 v[168:171], v165 offset:1024
	ds_read_b128 v[172:175], v165 offset:2048
	ds_read_b128 v[176:179], v165 offset:3072
	s_add_u32 s36, s34, 0xfffc0080
	s_addc_u32 s37, s35, -1
	s_cmp_eq_u32 s65, 12
	s_cselect_b32 s39, s25, s37
	s_cselect_b32 s38, s31, s36
	s_cselect_b32 s37, s23, s64
	s_cselect_b32 s36, s62, s63
	v_lshl_add_u64 v[212:213], s[34:35], 0, v[150:151]
	s_add_i32 m0, s45, 0xc000
	ds_read_b128 v[180:183], v166
	ds_read_b128 v[184:187], v166 offset:1024
	ds_read_b128 v[188:191], v166 offset:2048
	ds_read_b128 v[192:195], v166 offset:3072
	ds_read_b128 v[196:199], v166 offset:4096
	ds_read_b128 v[200:203], v166 offset:5120
	ds_read_b128 v[204:207], v166 offset:6144
	ds_read_b128 v[208:211], v166 offset:7168
	global_load_lds_dwordx4 v[212:213], off
	v_lshl_add_u64 v[212:213], s[34:35], 0, v[152:153]
	s_add_i32 m0, s45, 0xe000
	s_nop 0
	global_load_lds_dwordx4 v[212:213], off
	s_waitcnt vmcnt(8)
	s_waitcnt lgkmcnt(0)
	s_barrier
	s_setprio 1
	s_waitcnt lgkmcnt(0)
	v_mfma_f32_16x16x32_bf16 v[124:127], v[128:131], v[180:183], 0
	v_mfma_f32_16x16x32_bf16 v[120:123], v[136:139], v[180:183], 0
	v_mfma_f32_16x16x32_bf16 v[116:119], v[128:131], v[188:191], 0
	v_mfma_f32_16x16x32_bf16 v[112:115], v[136:139], v[188:191], 0
	v_mfma_f32_16x16x32_bf16 v[108:111], v[128:131], v[196:199], 0
	v_mfma_f32_16x16x32_bf16 v[100:103], v[136:139], v[196:199], 0
	v_mfma_f32_16x16x32_bf16 v[92:95], v[128:131], v[204:207], 0
	v_mfma_f32_16x16x32_bf16 v[76:79], v[136:139], v[204:207], 0
	v_mfma_f32_16x16x32_bf16 v[124:127], v[132:135], v[184:187], v[124:127]
	v_mfma_f32_16x16x32_bf16 v[120:123], v[140:143], v[184:187], v[120:123]
	v_mfma_f32_16x16x32_bf16 v[116:119], v[132:135], v[192:195], v[116:119]
	v_mfma_f32_16x16x32_bf16 v[112:115], v[140:143], v[192:195], v[112:115]
	v_mfma_f32_16x16x32_bf16 v[108:111], v[132:135], v[200:203], v[108:111]
	v_mfma_f32_16x16x32_bf16 v[100:103], v[140:143], v[200:203], v[100:103]
	v_mfma_f32_16x16x32_bf16 v[92:95], v[132:135], v[208:211], v[92:95]
	v_mfma_f32_16x16x32_bf16 v[76:79], v[140:143], v[208:211], v[76:79]
	s_setprio 0
	s_setprio 1
	v_mfma_f32_16x16x32_bf16 v[104:107], v[158:161], v[180:183], 0
	v_mfma_f32_16x16x32_bf16 v[96:99], v[172:175], v[180:183], 0
	v_mfma_f32_16x16x32_bf16 v[88:91], v[158:161], v[188:191], 0
	v_mfma_f32_16x16x32_bf16 v[84:87], v[172:175], v[188:191], 0
	v_mfma_f32_16x16x32_bf16 v[80:83], v[158:161], v[196:199], 0
	v_mfma_f32_16x16x32_bf16 v[72:75], v[172:175], v[196:199], 0
	v_mfma_f32_16x16x32_bf16 v[68:71], v[158:161], v[204:207], 0
	v_mfma_f32_16x16x32_bf16 v[64:67], v[172:175], v[204:207], 0
	v_mfma_f32_16x16x32_bf16 v[104:107], v[168:171], v[184:187], v[104:107]
	v_mfma_f32_16x16x32_bf16 v[96:99], v[176:179], v[184:187], v[96:99]
	v_mfma_f32_16x16x32_bf16 v[88:91], v[168:171], v[192:195], v[88:91]
	v_mfma_f32_16x16x32_bf16 v[84:87], v[176:179], v[192:195], v[84:87]
	v_mfma_f32_16x16x32_bf16 v[80:83], v[168:171], v[200:203], v[80:83]
	v_mfma_f32_16x16x32_bf16 v[72:75], v[176:179], v[200:203], v[72:75]
	v_mfma_f32_16x16x32_bf16 v[68:71], v[168:171], v[208:211], v[68:71]
	v_mfma_f32_16x16x32_bf16 v[64:67], v[176:179], v[208:211], v[64:67]
	s_setprio 0
	s_barrier
	s_add_i32 s66, s55, s44
	v_lshl_add_u64 v[212:213], s[36:37], 0, v[144:145]
	s_mov_b32 m0, s66
	ds_read_b128 v[180:183], v166 offset:16384
	ds_read_b128 v[184:187], v166 offset:17408
	ds_read_b128 v[188:191], v166 offset:18432
	ds_read_b128 v[192:195], v166 offset:19456
	ds_read_b128 v[196:199], v166 offset:20480
	ds_read_b128 v[200:203], v166 offset:21504
	ds_read_b128 v[204:207], v166 offset:22528
	ds_read_b128 v[208:211], v166 offset:23552
	global_load_lds_dwordx4 v[212:213], off
	s_add_i32 m0, s66, 0x2000
	s_add_u32 s66, s36, 0x40000
	v_lshl_add_u64 v[214:215], s[36:37], 0, v[146:147]
	s_addc_u32 s67, s37, 0
	s_add_i32 s68, s56, s44
	global_load_lds_dwordx4 v[214:215], off
	v_lshl_add_u64 v[216:217], s[66:67], 0, v[144:145]
	s_mov_b32 m0, s68
	v_lshl_add_u64 v[218:219], s[38:39], 0, v[146:147]
	global_load_lds_dwordx4 v[216:217], off
	v_lshl_add_u64 v[216:217], s[66:67], 0, v[146:147]
	s_add_i32 m0, s68, 0x2000
	s_nop 0
	global_load_lds_dwordx4 v[216:217], off
	v_lshl_add_u64 v[216:217], s[38:39], 0, v[144:145]
	s_mov_b32 m0, s45
	s_nop 0
	global_load_lds_dwordx4 v[216:217], off
	s_mov_b32 m0, s46
	s_nop 0
	global_load_lds_dwordx4 v[218:219], off
	s_waitcnt vmcnt(8)
	s_waitcnt lgkmcnt(0)
	s_barrier
; #define PG8_STAGE(bufoff, gbase, voff) do { _Pragma("unroll") for (int _i = 0; _i < 2; ++_i) \
;         __builtin_amdgcn_global_load_lds((const unsigned*)((const char*)(gbase) + (voff)[_i]), (PG8_LAS unsigned*)(lds + (bufoff) + ldsw + _i * 8192), 16, 0, 0); } while (0)
; #define PG8_LDA(dst, b, h) do { _Pragma("unroll") for (int m = 0; m < 4; ++m) _Pragma("unroll") for (int k = 0; k < 2; ++k) dst[m][k] = *(const PG8_LAS bf16x8*)(lds + PG8_SA(b, h) + aoff + m * 2048 + k * 1024); } while (0)
; #define PG8_LDB(dst, b, h) do { _Pragma("unroll") for (int n = 0; n < 2; ++n) _Pragma("unroll") for (int k = 0; k < 2; ++k) dst[n][k] = *(const PG8_LAS bf16x8*)(lds + PG8_SB(b, h) + boff + n * 2048 + k * 1024); } while (0)
; #define PG8_MMA(ai, bj, At, Bt) do { __builtin_amdgcn_s_setprio(1); _Pragma("unroll") for (int m = 0; m < 4; ++m) _Pragma("unroll") for (int n = 0; n < 2; ++n) _Pragma("unroll") for (int k = 0; k < 2; ++k) \
;         acc[ai][bj][m][n] = __builtin_amdgcn_mfma_f32_16x16x32_bf16(Bt[n][k], At[m][k], acc[ai][bj][m][n], 0, 0, 0); __builtin_amdgcn_s_setprio(0); } while (0)
; #define PG8_WAIT_V(n) asm volatile("s_waitcnt vmcnt(" #n ")" ::: "memory")
; #define PG8_WAIT_L(n) asm volatile("s_waitcnt lgkmcnt(" #n ")" ::: "memory")
; #define PG8_BAR __builtin_amdgcn_s_barrier()
; #define PG8_SCHED __builtin_amdgcn_sched_barrier(0)
; template <class Epi, class Sched, bool ALIGN_EPI = false, bool SP2 = false>
; __device__ __forceinline__ void gemm_phase(PG8_LAS unsigned char* lds, const Gemm g, const Sched& S, const Epi& E) {
;     ...
;             PG8_WAIT_V(8); PG8_WAIT_L(0); PG8_BAR; PG8_MMA(1, 0, At, B0); PG8_MMA(1, 1, At, B1); PG8_BAR; PG8_SCHED;
;             PG8_LDB(B0, 1, 0); PG8_LDB(B1, 1, 1); PG8_SCHED; PG8_LDA(At, 1, 0); PG8_STAGE(PG8_SA(0, 1), a2 + hstep, voffA);
;             PG8_WAIT_V(8); PG8_WAIT_L(0); PG8_BAR; PG8_MMA(0, 0, At, B0); PG8_MMA(0, 1, At, B1); PG8_BAR; PG8_SCHED;
;             PG8_LDA(At, 1, 1); PG8_STAGE(PG8_SB(1, 0), b3, voffB); PG8_STAGE(PG8_SB(1, 1), b3 + hstep, voffB); PG8_STAGE(PG8_SA(1, 0), a3, voffA);
	s_setprio 1
	s_waitcnt lgkmcnt(0)
	v_mfma_f32_16x16x32_bf16 v[60:63], v[128:131], v[180:183], 0
	v_mfma_f32_16x16x32_bf16 v[56:59], v[136:139], v[180:183], 0
	v_mfma_f32_16x16x32_bf16 v[52:55], v[128:131], v[188:191], 0
	v_mfma_f32_16x16x32_bf16 v[48:51], v[136:139], v[188:191], 0
	v_mfma_f32_16x16x32_bf16 v[32:35], v[128:131], v[196:199], 0
	v_mfma_f32_16x16x32_bf16 v[24:27], v[136:139], v[196:199], 0
	v_mfma_f32_16x16x32_bf16 v[20:23], v[128:131], v[204:207], 0
	v_mfma_f32_16x16x32_bf16 v[8:11], v[136:139], v[204:207], 0
	v_mfma_f32_16x16x32_bf16 v[60:63], v[132:135], v[184:187], v[60:63]
	v_mfma_f32_16x16x32_bf16 v[56:59], v[140:143], v[184:187], v[56:59]
	v_mfma_f32_16x16x32_bf16 v[52:55], v[132:135], v[192:195], v[52:55]
	v_mfma_f32_16x16x32_bf16 v[48:51], v[140:143], v[192:195], v[48:51]
	v_mfma_f32_16x16x32_bf16 v[32:35], v[132:135], v[200:203], v[32:35]
	v_mfma_f32_16x16x32_bf16 v[24:27], v[140:143], v[200:203], v[24:27]
	v_mfma_f32_16x16x32_bf16 v[20:23], v[132:135], v[208:211], v[20:23]
	v_mfma_f32_16x16x32_bf16 v[8:11], v[140:143], v[208:211], v[8:11]
	s_setprio 0
	s_setprio 1
	v_mfma_f32_16x16x32_bf16 v[44:47], v[158:161], v[180:183], 0
	v_mfma_f32_16x16x32_bf16 v[40:43], v[172:175], v[180:183], 0
	v_mfma_f32_16x16x32_bf16 v[36:39], v[158:161], v[188:191], 0
	v_mfma_f32_16x16x32_bf16 v[28:31], v[172:175], v[188:191], 0
	v_mfma_f32_16x16x32_bf16 v[16:19], v[158:161], v[196:199], 0
	v_mfma_f32_16x16x32_bf16 v[12:15], v[172:175], v[196:199], 0
	v_mfma_f32_16x16x32_bf16 v[4:7], v[158:161], v[204:207], 0
	v_mfma_f32_16x16x32_bf16 v[0:3], v[172:175], v[204:207], 0
	v_mfma_f32_16x16x32_bf16 v[44:47], v[168:171], v[184:187], v[44:47]
	v_mfma_f32_16x16x32_bf16 v[40:43], v[176:179], v[184:187], v[40:43]
	v_mfma_f32_16x16x32_bf16 v[36:39], v[168:171], v[192:195], v[36:39]
	v_mfma_f32_16x16x32_bf16 v[28:31], v[176:179], v[192:195], v[28:31]
	v_mfma_f32_16x16x32_bf16 v[16:19], v[168:171], v[200:203], v[16:19]
	v_mfma_f32_16x16x32_bf16 v[12:15], v[176:179], v[200:203], v[12:15]
	v_mfma_f32_16x16x32_bf16 v[4:7], v[168:171], v[208:211], v[4:7]
	v_mfma_f32_16x16x32_bf16 v[0:3], v[176:179], v[208:211], v[0:3]
	s_setprio 0
	s_barrier
	s_add_i32 s66, 0, 0x18000
	s_add_i32 s67, 0, 0x1c000
	v_add_u32_e32 v140, s66, v162
	v_add_u32_e32 v167, s67, v162
	ds_read_b128 v[128:131], v140
	ds_read_b128 v[132:135], v140 offset:1024
	ds_read_b128 v[136:139], v140 offset:2048
	ds_read_b128 v[140:143], v140 offset:3072
	ds_read_b128 v[158:161], v167
	ds_read_b128 v[168:171], v167 offset:1024
	ds_read_b128 v[172:175], v167 offset:2048
	ds_read_b128 v[176:179], v167 offset:3072
	s_add_u32 s38, s38, 0x40000
	s_addc_u32 s39, s39, 0
	s_mov_b32 m0, s47
	v_lshl_add_u64 v[220:221], s[38:39], 0, v[144:145]
	ds_read_b128 v[180:183], v166 offset:32768
	ds_read_b128 v[184:187], v166 offset:33792
	ds_read_b128 v[188:191], v166 offset:34816
	ds_read_b128 v[192:195], v166 offset:35840
	ds_read_b128 v[196:199], v166 offset:36864
	ds_read_b128 v[200:203], v166 offset:37888
	ds_read_b128 v[204:207], v166 offset:38912
	ds_read_b128 v[208:211], v166 offset:39936
	global_load_lds_dwordx4 v[220:221], off
	v_lshl_add_u64 v[220:221], s[38:39], 0, v[146:147]
	s_mov_b32 m0, s48
	s_nop 0
	global_load_lds_dwordx4 v[220:221], off
	s_waitcnt vmcnt(8)
	s_waitcnt lgkmcnt(0)
	s_barrier
	s_setprio 1
	s_waitcnt lgkmcnt(0)
	v_mfma_f32_16x16x32_bf16 v[124:127], v[128:131], v[180:183], v[124:127]
	v_mfma_f32_16x16x32_bf16 v[120:123], v[136:139], v[180:183], v[120:123]
	v_mfma_f32_16x16x32_bf16 v[116:119], v[128:131], v[188:191], v[116:119]
	v_mfma_f32_16x16x32_bf16 v[112:115], v[136:139], v[188:191], v[112:115]
	v_mfma_f32_16x16x32_bf16 v[108:111], v[128:131], v[196:199], v[108:111]
	v_mfma_f32_16x16x32_bf16 v[100:103], v[136:139], v[196:199], v[100:103]
	v_mfma_f32_16x16x32_bf16 v[92:95], v[128:131], v[204:207], v[92:95]
	v_mfma_f32_16x16x32_bf16 v[76:79], v[136:139], v[204:207], v[76:79]
	v_mfma_f32_16x16x32_bf16 v[124:127], v[132:135], v[184:187], v[124:127]
	v_mfma_f32_16x16x32_bf16 v[120:123], v[140:143], v[184:187], v[120:123]
	v_mfma_f32_16x16x32_bf16 v[116:119], v[132:135], v[192:195], v[116:119]
	v_mfma_f32_16x16x32_bf16 v[112:115], v[140:143], v[192:195], v[112:115]
	v_mfma_f32_16x16x32_bf16 v[108:111], v[132:135], v[200:203], v[108:111]
	v_mfma_f32_16x16x32_bf16 v[100:103], v[140:143], v[200:203], v[100:103]
	v_mfma_f32_16x16x32_bf16 v[92:95], v[132:135], v[208:211], v[92:95]
	v_mfma_f32_16x16x32_bf16 v[76:79], v[140:143], v[208:211], v[76:79]
	s_setprio 0
	s_setprio 1
	v_mfma_f32_16x16x32_bf16 v[104:107], v[158:161], v[180:183], v[104:107]
	v_mfma_f32_16x16x32_bf16 v[96:99], v[172:175], v[180:183], v[96:99]
	v_mfma_f32_16x16x32_bf16 v[88:91], v[158:161], v[188:191], v[88:91]
	v_mfma_f32_16x16x32_bf16 v[84:87], v[172:175], v[188:191], v[84:87]
	v_mfma_f32_16x16x32_bf16 v[80:83], v[158:161], v[196:199], v[80:83]
	v_mfma_f32_16x16x32_bf16 v[72:75], v[172:175], v[196:199], v[72:75]
	v_mfma_f32_16x16x32_bf16 v[68:71], v[158:161], v[204:207], v[68:71]
	v_mfma_f32_16x16x32_bf16 v[64:67], v[172:175], v[204:207], v[64:67]
	v_mfma_f32_16x16x32_bf16 v[104:107], v[168:171], v[184:187], v[104:107]
	v_mfma_f32_16x16x32_bf16 v[96:99], v[176:179], v[184:187], v[96:99]
	v_mfma_f32_16x16x32_bf16 v[88:91], v[168:171], v[192:195], v[88:91]
	v_mfma_f32_16x16x32_bf16 v[84:87], v[176:179], v[192:195], v[84:87]
	v_mfma_f32_16x16x32_bf16 v[80:83], v[168:171], v[200:203], v[80:83]
	v_mfma_f32_16x16x32_bf16 v[72:75], v[176:179], v[200:203], v[72:75]
	v_mfma_f32_16x16x32_bf16 v[68:71], v[168:171], v[208:211], v[68:71]
	v_mfma_f32_16x16x32_bf16 v[64:67], v[176:179], v[208:211], v[64:67]
	s_setprio 0
	s_barrier
; #define PG8_STAGE(bufoff, gbase, voff) do { _Pragma("unroll") for (int _i = 0; _i < 2; ++_i) \
;         __builtin_amdgcn_global_load_lds((const unsigned*)((const char*)(gbase) + (voff)[_i]), (PG8_LAS unsigned*)(lds + (bufoff) + ldsw + _i * 8192), 16, 0, 0); } while (0)
; #define PG8_LDA(dst, b, h) do { _Pragma("unroll") for (int m = 0; m < 4; ++m) _Pragma("unroll") for (int k = 0; k < 2; ++k) dst[m][k] = *(const PG8_LAS bf16x8*)(lds + PG8_SA(b, h) + aoff + m * 2048 + k * 1024); } while (0)
; #define PG8_LDB(dst, b, h) do { _Pragma("unroll") for (int n = 0; n < 2; ++n) _Pragma("unroll") for (int k = 0; k < 2; ++k) dst[n][k] = *(const PG8_LAS bf16x8*)(lds + PG8_SB(b, h) + boff + n * 2048 + k * 1024); } while (0)
; #define PG8_MMA(ai, bj, At, Bt) do { __builtin_amdgcn_s_setprio(1); _Pragma("unroll") for (int m = 0; m < 4; ++m) _Pragma("unroll") for (int n = 0; n < 2; ++n) _Pragma("unroll") for (int k = 0; k < 2; ++k) \
;         acc[ai][bj][m][n] = __builtin_amdgcn_mfma_f32_16x16x32_bf16(Bt[n][k], At[m][k], acc[ai][bj][m][n], 0, 0, 0); __builtin_amdgcn_s_setprio(0); } while (0)
; #define PG8_WAIT_V(n) asm volatile("s_waitcnt vmcnt(" #n ")" ::: "memory")
; #define PG8_WAIT_L(n) asm volatile("s_waitcnt lgkmcnt(" #n ")" ::: "memory")
; #define PG8_BAR __builtin_amdgcn_s_barrier()
; #define PG8_SCHED __builtin_amdgcn_sched_barrier(0)
; template <class Epi, class Sched, bool ALIGN_EPI = false, bool SP2 = false>
; __device__ __forceinline__ void gemm_phase(PG8_LAS unsigned char* lds, const Gemm g, const Sched& S, const Epi& E) {
;     ...
;             PG8_WAIT_V(8); PG8_WAIT_L(0); PG8_BAR; PG8_MMA(1, 0, At, B0); PG8_MMA(1, 1, At, B1); PG8_BAR; PG8_SCHED;
;             PG8_LDB(B0, 1, 0); PG8_LDB(B1, 1, 1); PG8_SCHED; PG8_LDA(At, 1, 0); PG8_STAGE(PG8_SA(0, 1), a2 + hstep, voffA);
;             PG8_WAIT_V(8); PG8_WAIT_L(0); PG8_BAR; PG8_MMA(0, 0, At, B0); PG8_MMA(0, 1, At, B1); PG8_BAR; PG8_SCHED;
;             PG8_LDA(At, 1, 1); PG8_STAGE(PG8_SB(1, 0), b3, voffB); PG8_STAGE(PG8_SB(1, 1), b3 + hstep, voffB); PG8_STAGE(PG8_SA(1, 0), a3, voffA);
;             PG8_WAIT_V(8); PG8_WAIT_L(0); PG8_BAR; PG8_MMA(1, 0, At, B0); PG8_MMA(1, 1, At, B1); PG8_BAR; PG8_SCHED;
	s_add_i32 s38, s66, s44
	v_lshl_add_u64 v[212:213], v[212:213], 0, s[10:11]
	s_mov_b32 m0, s38
	ds_read_b128 v[180:183], v166 offset:49152
	ds_read_b128 v[184:187], v166 offset:50176
	ds_read_b128 v[188:191], v166 offset:51200
	ds_read_b128 v[192:195], v166 offset:52224
	ds_read_b128 v[196:199], v166 offset:53248
	ds_read_b128 v[200:203], v166 offset:54272
	ds_read_b128 v[204:207], v166 offset:55296
	ds_read_b128 v[208:211], v166 offset:56320
	global_load_lds_dwordx4 v[212:213], off
	s_add_i32 m0, s38, 0x2000
	s_add_u32 s36, s36, 0x40080
	v_lshl_add_u64 v[212:213], v[214:215], 0, s[10:11]
	s_addc_u32 s37, s37, 0
	s_add_i32 s38, s67, s44
	global_load_lds_dwordx4 v[212:213], off
	v_lshl_add_u64 v[212:213], s[36:37], 0, v[144:145]
	s_mov_b32 m0, s38
	s_nop 0
	global_load_lds_dwordx4 v[212:213], off
	v_lshl_add_u64 v[212:213], s[36:37], 0, v[146:147]
	s_add_i32 m0, s38, 0x2000
	s_nop 0
	global_load_lds_dwordx4 v[212:213], off
	v_lshl_add_u64 v[212:213], v[216:217], 0, s[10:11]
	s_mov_b32 m0, s52
	s_nop 0
	global_load_lds_dwordx4 v[212:213], off
	v_lshl_add_u64 v[212:213], v[218:219], 0, s[10:11]
	s_mov_b32 m0, s53
	s_nop 0
	global_load_lds_dwordx4 v[212:213], off
	s_waitcnt vmcnt(8)
	s_waitcnt lgkmcnt(0)
	s_barrier
	s_setprio 1
	s_waitcnt lgkmcnt(0)
	v_mfma_f32_16x16x32_bf16 v[60:63], v[128:131], v[180:183], v[60:63]
	v_mfma_f32_16x16x32_bf16 v[56:59], v[136:139], v[180:183], v[56:59]
	v_mfma_f32_16x16x32_bf16 v[52:55], v[128:131], v[188:191], v[52:55]
	v_mfma_f32_16x16x32_bf16 v[48:51], v[136:139], v[188:191], v[48:51]
	v_mfma_f32_16x16x32_bf16 v[32:35], v[128:131], v[196:199], v[32:35]
	v_mfma_f32_16x16x32_bf16 v[24:27], v[136:139], v[196:199], v[24:27]
	v_mfma_f32_16x16x32_bf16 v[20:23], v[128:131], v[204:207], v[20:23]
	v_mfma_f32_16x16x32_bf16 v[8:11], v[136:139], v[204:207], v[8:11]
	v_mfma_f32_16x16x32_bf16 v[60:63], v[132:135], v[184:187], v[60:63]
	v_mfma_f32_16x16x32_bf16 v[56:59], v[140:143], v[184:187], v[56:59]
	v_mfma_f32_16x16x32_bf16 v[52:55], v[132:135], v[192:195], v[52:55]
	v_mfma_f32_16x16x32_bf16 v[48:51], v[140:143], v[192:195], v[48:51]
	v_mfma_f32_16x16x32_bf16 v[32:35], v[132:135], v[200:203], v[32:35]
	v_mfma_f32_16x16x32_bf16 v[24:27], v[140:143], v[200:203], v[24:27]
	v_mfma_f32_16x16x32_bf16 v[20:23], v[132:135], v[208:211], v[20:23]
	v_mfma_f32_16x16x32_bf16 v[8:11], v[140:143], v[208:211], v[8:11]
	s_setprio 0
	s_setprio 1
	v_mfma_f32_16x16x32_bf16 v[44:47], v[158:161], v[180:183], v[44:47]
	v_mfma_f32_16x16x32_bf16 v[40:43], v[172:175], v[180:183], v[40:43]
	v_mfma_f32_16x16x32_bf16 v[36:39], v[158:161], v[188:191], v[36:39]
	v_mfma_f32_16x16x32_bf16 v[28:31], v[172:175], v[188:191], v[28:31]
	v_mfma_f32_16x16x32_bf16 v[16:19], v[158:161], v[196:199], v[16:19]
	v_mfma_f32_16x16x32_bf16 v[12:15], v[172:175], v[196:199], v[12:15]
	v_mfma_f32_16x16x32_bf16 v[4:7], v[158:161], v[204:207], v[4:7]
	v_mfma_f32_16x16x32_bf16 v[0:3], v[172:175], v[204:207], v[0:3]
	v_mfma_f32_16x16x32_bf16 v[44:47], v[168:171], v[184:187], v[44:47]
	v_mfma_f32_16x16x32_bf16 v[40:43], v[176:179], v[184:187], v[40:43]
	v_mfma_f32_16x16x32_bf16 v[36:39], v[168:171], v[192:195], v[36:39]
	v_mfma_f32_16x16x32_bf16 v[28:31], v[176:179], v[192:195], v[28:31]
	v_mfma_f32_16x16x32_bf16 v[16:19], v[168:171], v[200:203], v[16:19]
	v_mfma_f32_16x16x32_bf16 v[12:15], v[176:179], v[200:203], v[12:15]
	v_mfma_f32_16x16x32_bf16 v[4:7], v[168:171], v[208:211], v[4:7]
	v_mfma_f32_16x16x32_bf16 v[0:3], v[176:179], v[208:211], v[0:3]
	s_setprio 0
	s_barrier
	s_add_i32 s65, s65, 2
	s_add_u32 s34, s34, 0x100
	s_addc_u32 s35, s35, 0
	s_add_u32 s63, s63, 0x100
	s_addc_u32 s64, s64, 0
	s_cmp_gt_u32 s65, 13
	.p2align	6
